# same 1/x -> v_rcp_f32 replacement applied to the gates GEMM epilogue sigmoids, POST z*sigmoid(z) loop and the LSE-merge normalisation
# speedup vs baseline: 1.0571x; 1.0058x over previous
.LBB0_758:
	v_ashrrev_i32_e32 v14, 6, v13
	v_ashrrev_i32_e32 v15, 31, v14
	v_lshlrev_b64 v[16:17], 5, v[14:15]
	v_lshl_add_u64 v[16:17], v[2:3], 0, v[16:17]
	v_lshl_add_u64 v[18:19], v[14:15], 0, s[48:49]
	global_load_dword v20, v[16:17], off
	v_lshlrev_b64 v[16:17], 5, v[18:19]
	v_lshl_add_u64 v[16:17], v[2:3], 0, v[16:17]
	v_lshl_add_u64 v[22:23], v[14:15], 0, s[46:47]
	global_load_dword v21, v[16:17], off
	v_lshlrev_b64 v[16:17], 5, v[22:23]
	v_lshl_add_u64 v[16:17], v[2:3], 0, v[16:17]
	global_load_dword v16, v[16:17], off
	v_lshlrev_b64 v[32:33], 10, v[14:15]
	v_lshlrev_b64 v[18:19], 10, v[18:19]
	v_lshl_add_u64 v[14:15], v[8:9], 0, v[32:33]
	v_lshl_add_u64 v[18:19], v[8:9], 0, v[18:19]
	v_lshlrev_b64 v[22:23], 10, v[22:23]
	v_lshl_add_u64 v[22:23], v[8:9], 0, v[22:23]
	v_add_u32_e32 v13, s76, v13
	s_waitcnt vmcnt(0)
	v_max3_f32 v17, v20, v21, v16
	v_sub_f32_e32 v20, v20, v17
	v_exp_f32_e32 v27, v20
	v_sub_f32_e32 v20, v21, v17
	v_exp_f32_e32 v26, v20
	v_sub_f32_e32 v16, v16, v17
	v_exp_f32_e32 v16, v16
	v_add_f32_e32 v17, v27, v26
	v_add_f32_e32 v17, v16, v17
	s_nop 0
	s_nop 0
	s_mov_b32 s4, 0xfffff
	s_nop 0
	s_nop 0
	s_nop 0
	s_nop 0
	s_nop 0
	s_nop 0
	s_nop 0
	s_nop 0
	v_rcp_f32_e32 v28, v17
	s_nop 0
	v_mul_f32_e32 v30, v16, v28
	global_load_dwordx4 v[14:17], v[14:15], off nt
	v_pk_mul_f32 v[26:27], v[26:27], v[28:29] op_sel_hi:[1,0]
	global_load_dwordx4 v[18:21], v[18:19], off nt
	v_cmp_lt_i32_e32 vcc, s4, v13
	global_load_dwordx4 v[22:25], v[22:23], off nt
	s_or_b64 s[2:3], vcc, s[2:3]
	s_waitcnt vmcnt(2)
	v_lshlrev_b32_e32 v34, 16, v14
	v_and_b32_e32 v29, 0xffff0000, v14
	s_waitcnt vmcnt(1)
	v_and_b32_e32 v35, 0xffff0000, v18
	v_lshlrev_b32_e32 v28, 16, v18
	v_pk_mul_f32 v[34:35], v[26:27], v[34:35] op_sel:[1,0] op_sel_hi:[0,1]
	s_waitcnt vmcnt(0)
	v_lshlrev_b32_e32 v36, 16, v22
	v_and_b32_e32 v37, 0xffff0000, v22
	v_pk_fma_f32 v[28:29], v[26:27], v[28:29], v[34:35]
	v_lshlrev_b32_e32 v18, 16, v15
	v_pk_fma_f32 v[28:29], v[30:31], v[36:37], v[28:29] op_sel_hi:[0,1,1]
	v_cvt_pk_bf16_f32 v14, v28, v29
	v_lshlrev_b32_e32 v28, 16, v19
	v_and_b32_e32 v19, 0xffff0000, v19
	v_and_b32_e32 v29, 0xffff0000, v15
	v_pk_mul_f32 v[18:19], v[26:27], v[18:19] op_sel:[1,0] op_sel_hi:[0,1]
	v_lshlrev_b32_e32 v22, 16, v23
	v_and_b32_e32 v23, 0xffff0000, v23
	v_pk_fma_f32 v[18:19], v[26:27], v[28:29], v[18:19]
	v_lshlrev_b32_e32 v28, 16, v24
	v_pk_fma_f32 v[18:19], v[30:31], v[22:23], v[18:19] op_sel_hi:[0,1,1]
	v_lshlrev_b32_e32 v22, 16, v16
	v_and_b32_e32 v23, 0xffff0000, v20
	v_cvt_pk_bf16_f32 v15, v18, v19
	v_lshlrev_b32_e32 v18, 16, v20
	v_and_b32_e32 v19, 0xffff0000, v16
	v_pk_mul_f32 v[22:23], v[26:27], v[22:23] op_sel:[1,0] op_sel_hi:[0,1]
	v_and_b32_e32 v29, 0xffff0000, v24
	v_pk_fma_f32 v[18:19], v[26:27], v[18:19], v[22:23]
	v_lshlrev_b32_e32 v20, 16, v17
	v_pk_fma_f32 v[18:19], v[30:31], v[28:29], v[18:19] op_sel_hi:[0,1,1]
	v_cvt_pk_bf16_f32 v16, v18, v19
	v_lshlrev_b32_e32 v18, 16, v21
	v_and_b32_e32 v21, 0xffff0000, v21
	v_and_b32_e32 v19, 0xffff0000, v17
	v_pk_mul_f32 v[20:21], v[26:27], v[20:21] op_sel:[1,0] op_sel_hi:[0,1]
	v_pk_fma_f32 v[18:19], v[26:27], v[18:19], v[20:21]
	v_lshlrev_b32_e32 v20, 16, v25
	v_and_b32_e32 v21, 0xffff0000, v25
	v_pk_fma_f32 v[18:19], v[30:31], v[20:21], v[18:19] op_sel_hi:[0,1,1]
	v_cvt_pk_bf16_f32 v17, v18, v19
	v_lshl_add_u64 v[18:19], v[10:11], 0, v[32:33]
	global_store_dwordx4 v[18:19], v[14:17], off nt
	s_andn2_b64 exec, exec, s[2:3]
	s_cbranch_execnz .LBB0_758

.LBB0_761:
	v_ashrrev_i32_e32 v12, 7, v1
	v_ashrrev_i32_e32 v13, 31, v12
	v_lshlrev_b64 v[28:29], 11, v[12:13]
	v_and_b32_e32 v14, 0x3f8, v10
	v_lshl_add_u64 v[12:13], s[2:3], 0, v[28:29]
	v_lshlrev_b32_e32 v30, 1, v14
	v_mov_b32_e32 v31, v0
	v_lshl_add_u64 v[12:13], v[12:13], 0, v[30:31]
	global_load_dwordx4 v[12:15], v[12:13], off nt
	v_lshl_add_u64 v[16:17], s[4:5], 0, v[28:29]
	v_lshl_add_u64 v[16:17], v[16:17], 0, v[30:31]
	global_load_dwordx4 v[16:19], v[16:17], off nt
	v_and_b32_e32 v11, 0x78, v10
	v_lshlrev_b32_e32 v11, 2, v11
	global_load_dwordx4 v[20:23], v11, s[12:13] offset:16
	global_load_dwordx4 v[24:27], v11, s[12:13]
	v_add_u32_e32 v1, s76, v1
	v_add_u32_e32 v10, s92, v10
	s_waitcnt vmcnt(3)
	v_and_b32_e32 v33, 0xffff0000, v15
	v_and_b32_e32 v37, 0xffff0000, v14
	v_lshlrev_b32_e32 v32, 16, v15
	v_lshlrev_b32_e32 v36, 16, v14
	v_mov_b32_e32 v38, v33
	v_mov_b32_e32 v39, v37
	v_mov_b32_e32 v14, v32
	v_mov_b32_e32 v15, v36
	v_pk_mul_f32 v[38:39], v[38:39], v[38:39]
	s_waitcnt vmcnt(2)
	v_lshlrev_b32_e32 v34, 16, v19
	v_pk_fma_f32 v[14:15], v[14:15], v[14:15], v[38:39]
	v_lshlrev_b32_e32 v38, 16, v18
	v_and_b32_e32 v39, 0xffff0000, v18
	v_mul_f32_e32 v11, 0xbfb8aa3b, v38
	v_exp_f32_e32 v18, v11
	v_mul_f32_e32 v11, 0xbfb8aa3b, v39
	v_and_b32_e32 v35, 0xffff0000, v19
	v_exp_f32_e32 v19, v11
	s_nop 0
	v_pk_add_f32 v[18:19], v[18:19], 1.0 op_sel_hi:[1,0]
	s_nop 0
	s_nop 0
	s_nop 0
	s_nop 0
	s_nop 0
	s_nop 0
	s_nop 0
	s_nop 0
	s_nop 0
	s_nop 0
	s_nop 0
	s_nop 0
	v_rcp_f32_e32 v19, v19
	s_nop 0
	s_nop 0
	s_nop 0
	s_nop 0
	s_nop 0
	s_nop 0
	s_nop 0
	s_nop 0
	s_nop 0
	s_nop 0
	s_nop 0
	v_lshlrev_b32_e32 v40, 16, v17
	v_rcp_f32_e32 v18, v18
	v_and_b32_e32 v41, 0xffff0000, v17
	v_mul_f32_e32 v11, 0xbfb8aa3b, v40
	v_exp_f32_e32 v42, v11
	v_mul_f32_e32 v11, 0xbfb8aa3b, v41
	v_exp_f32_e32 v43, v11
	v_pk_mul_f32 v[18:19], v[18:19], v[38:39]
	v_lshlrev_b32_e32 v38, 16, v13
	v_and_b32_e32 v39, 0xffff0000, v13
	v_pk_add_f32 v[42:43], v[42:43], 1.0 op_sel_hi:[1,0]
	s_nop 0
	s_nop 0
	s_nop 0
	s_nop 0
	s_nop 0
	s_nop 0
	s_nop 0
	s_nop 0
	s_nop 0
	s_nop 0
	s_nop 0
	s_nop 0
	v_rcp_f32_e32 v43, v43
	s_nop 0
	s_nop 0
	s_nop 0
	s_nop 0
	s_nop 0
	s_nop 0
	s_nop 0
	s_nop 0
	s_nop 0
	s_nop 0
	s_nop 0
	v_rcp_f32_e32 v42, v42
	s_nop 0
	v_pk_mul_f32 v[40:41], v[42:43], v[40:41]
	v_and_b32_e32 v43, 0xffff0000, v12
	v_lshlrev_b32_e32 v42, 16, v12
	v_mov_b32_e32 v44, v43
	v_mov_b32_e32 v45, v39
	v_mov_b32_e32 v12, v42
	v_mov_b32_e32 v13, v38
	v_pk_mul_f32 v[44:45], v[44:45], v[44:45]
	s_nop 0
	v_pk_fma_f32 v[12:13], v[12:13], v[12:13], v[44:45]
	v_lshlrev_b32_e32 v44, 16, v16
	v_and_b32_e32 v45, 0xffff0000, v16
	v_mul_f32_e32 v11, 0xbfb8aa3b, v44
	v_exp_f32_e32 v16, v11
	v_mul_f32_e32 v11, 0xbfb8aa3b, v45
	v_exp_f32_e32 v17, v11
	s_nop 0
	v_pk_add_f32 v[16:17], v[16:17], 1.0 op_sel_hi:[1,0]
	s_nop 0
	s_nop 0
	s_nop 0
	s_nop 0
	s_nop 0
	s_nop 0
	s_nop 0
	s_nop 0
	s_nop 0
	s_nop 0
	s_nop 0
	s_nop 0
	v_rcp_f32_e32 v17, v17
	s_nop 0
	s_nop 0
	s_nop 0
	s_nop 0
	s_nop 0
	s_nop 0
	s_nop 0
	s_nop 0
	s_nop 0
	s_nop 0
	s_nop 0
	v_rcp_f32_e32 v16, v16
	v_add_f32_e32 v11, v12, v13
	v_add_f32_e32 v11, v15, v11
	v_add_f32_e32 v11, v14, v11
	ds_bpermute_b32 v12, v2, v11
	v_pk_mul_f32 v[16:17], v[16:17], v[44:45]
	s_waitcnt lgkmcnt(0)
	v_add_f32_e32 v11, v11, v12
	ds_bpermute_b32 v12, v3, v11
	s_waitcnt lgkmcnt(0)
	v_add_f32_e32 v11, v11, v12
	ds_bpermute_b32 v12, v8, v11
	s_waitcnt lgkmcnt(0)
	v_add_f32_e32 v11, v11, v12
	ds_bpermute_b32 v12, v9, v11
	s_waitcnt lgkmcnt(0)
	v_add_f32_e32 v11, v11, v12
	v_fmamk_f32 v11, v11, 0x3c000000, v208
	v_cmp_gt_f32_e32 vcc, s51, v11
	v_mul_f32_e32 v12, 0x4b800000, v11
	s_nop 0
	v_cndmask_b32_e32 v11, v11, v12, vcc
	v_rsq_f32_e32 v11, v11
	s_nop 0
	v_mul_f32_e32 v12, 0x45800000, v11
	v_cndmask_b32_e32 v44, v11, v12, vcc
	v_pk_mul_f32 v[12:13], v[44:45], v[42:43] op_sel_hi:[0,1]
	s_waitcnt vmcnt(0)
	v_pk_mul_f32 v[12:13], v[24:25], v[12:13]
	v_mul_f32_e32 v11, 0xbfb8aa3b, v34
	v_pk_mul_f32 v[12:13], v[16:17], v[12:13]
	v_exp_f32_e32 v16, v11
	v_mul_f32_e32 v11, 0xbfb8aa3b, v35
	v_pk_mul_f32 v[14:15], v[44:45], v[38:39] op_sel_hi:[0,1]
	v_exp_f32_e32 v17, v11
	v_pk_mul_f32 v[14:15], v[26:27], v[14:15]
	v_cvt_pk_bf16_f32 v12, v12, v13
	v_pk_mul_f32 v[14:15], v[40:41], v[14:15]
	v_pk_add_f32 v[16:17], v[16:17], 1.0 op_sel_hi:[1,0]
	v_cvt_pk_bf16_f32 v13, v14, v15
	v_pk_mul_f32 v[14:15], v[44:45], v[36:37] op_sel_hi:[0,1]
	v_pk_mul_f32 v[14:15], v[20:21], v[14:15]
	s_nop 0
	v_pk_mul_f32 v[14:15], v[18:19], v[14:15]
	v_pk_mul_f32 v[18:19], v[44:45], v[32:33] op_sel_hi:[0,1]
	v_cvt_pk_bf16_f32 v14, v14, v15
	s_nop 0
	v_pk_mul_f32 v[18:19], v[22:23], v[18:19]
	s_nop 0
	s_nop 0
	s_nop 0
	s_nop 0
	s_nop 0
	s_nop 0
	s_nop 0
	s_nop 0
	v_rcp_f32_e32 v17, v17
	s_nop 0
	s_nop 0
	s_mov_b32 s10, 0x1fffff
	s_nop 0
	s_nop 0
	s_nop 0
	s_nop 0
	s_nop 0
	s_nop 0
	s_nop 0
	s_nop 0
	v_rcp_f32_e32 v16, v16
	s_nop 0
	v_pk_mul_f32 v[16:17], v[16:17], v[34:35]
	v_cmp_lt_i32_e32 vcc, s10, v1
	v_pk_mul_f32 v[16:17], v[16:17], v[18:19]
	s_or_b64 s[8:9], vcc, s[8:9]
	v_cvt_pk_bf16_f32 v15, v16, v17
	v_lshl_add_u64 v[16:17], s[6:7], 0, v[28:29]
	v_lshl_add_u64 v[16:17], v[16:17], 0, v[30:31]
	global_store_dwordx4 v[16:17], v[12:15], off nt
	s_andn2_b64 exec, exec, s[8:9]
	s_cbranch_execnz .LBB0_761

.LBB0_774:
	s_lshl_b32 s7, s37, 8
	s_ashr_i32 s9, s33, 2
	s_add_i32 s7, s7, s31
	s_lshl_b32 s14, s9, 10
	s_cmp_eq_u32 s9, 1
	s_mov_b32 s9, 0x1000000
	v_mov_b32_e32 v162, v1
	s_cselect_b32 s9, s9, 0x8600000
	s_cmp_gt_u32 s33, 3
	v_lshl_or_b32 v160, s33, 8, v186
	v_readlane_b32 s16, v251, 63
	v_add_u32_e32 v180, s7, v162
	s_cselect_b32 s7, s9, 0
	v_ashrrev_i32_e32 v161, 31, v160
	v_readlane_b32 s17, v252, 0
	s_lshl_b32 s7, s7, 1
	v_ashrrev_i32_e32 v181, 31, v180
	v_lshl_add_u64 v[28:29], v[160:161], 2, s[16:17]
	v_subrev_u32_e32 v160, s14, v160
	s_add_u32 s14, s29, s7
	s_addc_u32 s15, s30, 0
	v_ashrrev_i32_e32 v161, 31, v160
	v_lshl_add_u64 v[178:179], v[160:161], 1, s[14:15]
	v_lshlrev_b64 v[160:161], 6, v[180:181]
	v_lshl_add_u64 v[160:161], s[2:3], 0, v[160:161]
	global_load_dwordx4 v[40:43], v[28:29], off offset:16
	global_load_dwordx4 v[44:47], v[28:29], off
	global_load_dwordx4 v[24:27], v[28:29], off offset:528
	s_nop 0
	global_load_dwordx4 v[28:31], v[28:29], off offset:512
	s_nop 0
	global_load_dwordx4 v[188:191], v[160:161], off offset:16
	global_load_dwordx4 v[192:195], v[160:161], off offset:48
	global_load_dwordx4 v[196:199], v[160:161], off
	global_load_dwordx4 v[200:203], v[160:161], off offset:32
	s_mov_b64 s[48:49], 0x4000
	s_mov_b64 s[46:47], 0x8000
	s_waitcnt vmcnt(0)
	v_mov_b32_e32 v164, v190
	v_mov_b32_e32 v165, v194
	v_mov_b32_e32 v160, v196
	v_mov_b32_e32 v161, v200
	v_mov_b32_e32 v200, v197
	v_mov_b32_e32 v162, v198
	v_mov_b32_e32 v163, v202
	v_mov_b32_e32 v202, v199
	v_pk_add_f32 v[160:161], v[160:161], v[200:201]
	v_pk_add_f32 v[162:163], v[162:163], v[202:203]
	v_mov_b32_e32 v194, v191
	v_pk_add_f32 v[160:161], v[160:161], v[162:163]
	v_mov_b32_e32 v162, v188
	v_mov_b32_e32 v163, v192
	v_mov_b32_e32 v192, v189
	v_pk_add_f32 v[162:163], v[162:163], v[192:193]
	v_pk_add_f32 v[164:165], v[164:165], v[194:195]
	s_nop 0
	v_pk_add_f32 v[162:163], v[162:163], v[164:165]
	s_nop 0
	v_pk_add_f32 v[160:161], v[160:161], v[162:163]
	s_nop 0
	v_add_f32_e32 v160, v160, v161
	v_fmamk_f32 v160, v160, 0x3a800000, v208
	v_cmp_gt_f32_e32 vcc, s51, v160
	v_mul_f32_e32 v161, 0x4b800000, v160
	s_nop 0
	v_cndmask_b32_e32 v160, v160, v161, vcc
	v_rsq_f32_e32 v160, v160
	s_nop 0
	v_mul_f32_e32 v161, 0x45800000, v160
	v_cndmask_b32_e32 v184, v160, v161, vcc
	v_lshlrev_b64 v[160:161], 11, v[180:181]
	v_lshl_add_u64 v[182:183], v[178:179], 0, v[160:161]
	v_pk_fma_f32 v[160:161], v[148:149], v[184:185], v[44:45] op_sel_hi:[1,0,1]
	v_pk_fma_f32 v[148:149], v[146:147], v[184:185], v[42:43] op_sel_hi:[1,0,1]
	v_pk_fma_f32 v[146:147], v[144:145], v[184:185], v[40:41] op_sel_hi:[1,0,1]
	v_mul_f32_e32 v144, 0xbfb8aa3b, v160
	v_mul_f32_e32 v145, 0xbfb8aa3b, v161
	v_exp_f32_e32 v144, v144
	v_exp_f32_e32 v145, v145
	v_pk_fma_f32 v[150:151], v[150:151], v[184:185], v[46:47] op_sel_hi:[1,0,1]
	v_mul_f32_e32 v146, 0xbfb8aa3b, v146
	v_mul_f32_e32 v147, 0xbfb8aa3b, v147
	v_pk_add_f32 v[144:145], v[144:145], 1.0 op_sel_hi:[1,0]
	v_exp_f32_e32 v146, v146
	s_nop 0
	s_nop 0
	v_exp_f32_e32 v147, v147
	v_pk_fma_f32 v[142:143], v[142:143], v[184:185], v[30:31] op_sel_hi:[1,0,1]
	s_nop 0
	s_nop 0
	s_nop 0
	s_nop 0
	s_nop 0
	s_nop 0
	s_nop 0
	s_nop 0
	v_rcp_f32_e32 v145, v145
	s_nop 0
	s_nop 0
	v_pk_add_f32 v[146:147], v[146:147], 1.0 op_sel_hi:[1,0]
	s_nop 0
	s_nop 0
	s_nop 0
	s_nop 0
	s_nop 0
	s_nop 0
	s_nop 0
	s_nop 0
	v_rcp_f32_e32 v144, v144
	s_nop 0
	v_cvt_pk_bf16_f32 v144, v144, v145
	v_mul_f32_e32 v145, 0xbfb8aa3b, v150
	v_exp_f32_e32 v150, v145
	v_mul_f32_e32 v145, 0xbfb8aa3b, v151
	v_exp_f32_e32 v151, v145
	s_nop 0
	v_pk_add_f32 v[150:151], v[150:151], 1.0 op_sel_hi:[1,0]
	s_nop 0
	s_nop 0
	s_nop 0
	s_nop 0
	s_nop 0
	s_nop 0
	s_nop 0
	s_nop 0
	s_nop 0
	s_nop 0
	s_nop 0
	s_nop 0
	v_rcp_f32_e32 v145, v151
	s_nop 0
	s_nop 0
	s_nop 0
	s_nop 0
	s_nop 0
	s_nop 0
	s_nop 0
	s_nop 0
	s_nop 0
	s_nop 0
	s_nop 0
	v_rcp_f32_e32 v150, v150
	s_nop 0
	v_cvt_pk_bf16_f32 v145, v150, v145
	s_nop 0
	s_nop 0
	s_nop 0
	s_nop 0
	s_nop 0
	s_nop 0
	s_nop 0
	s_nop 0
	s_nop 0
	s_nop 0
	s_nop 0
	v_rcp_f32_e32 v147, v147
	s_nop 0
	s_nop 0
	s_nop 0
	s_nop 0
	s_nop 0
	s_nop 0
	s_nop 0
	s_nop 0
	s_nop 0
	s_nop 0
	s_nop 0
	v_rcp_f32_e32 v146, v146
	s_nop 0
	v_cvt_pk_bf16_f32 v146, v146, v147
	v_mul_f32_e32 v147, 0xbfb8aa3b, v148
	v_exp_f32_e32 v148, v147
	v_mul_f32_e32 v147, 0xbfb8aa3b, v149
	v_exp_f32_e32 v149, v147
	s_nop 0
	v_pk_add_f32 v[148:149], v[148:149], 1.0 op_sel_hi:[1,0]
	s_nop 0
	s_nop 0
	s_nop 0
	s_nop 0
	s_nop 0
	s_nop 0
	s_nop 0
	s_nop 0
	s_nop 0
	s_nop 0
	s_nop 0
	s_nop 0
	v_rcp_f32_e32 v147, v149
	s_nop 0
	s_nop 0
	s_nop 0
	s_nop 0
	s_nop 0
	s_nop 0
	s_nop 0
	s_nop 0
	s_nop 0
	s_nop 0
	s_nop 0
	v_rcp_f32_e32 v148, v148
	s_nop 0
	v_cvt_pk_bf16_f32 v147, v148, v147
	global_store_dwordx4 v[182:183], v[144:147], off
	v_add_u32_e32 v160, 16, v180
	v_ashrrev_i32_e32 v161, 31, v160
	v_pk_fma_f32 v[144:145], v[140:141], v[184:185], v[28:29] op_sel_hi:[1,0,1]
	v_pk_fma_f32 v[140:141], v[138:139], v[184:185], v[26:27] op_sel_hi:[1,0,1]
	v_pk_fma_f32 v[138:139], v[136:137], v[184:185], v[24:25] op_sel_hi:[1,0,1]
	v_mul_f32_e32 v136, 0xbfb8aa3b, v144
	v_mul_f32_e32 v137, 0xbfb8aa3b, v145
	v_exp_f32_e32 v136, v136
	v_exp_f32_e32 v137, v137
	v_mul_f32_e32 v138, 0xbfb8aa3b, v138
	v_mul_f32_e32 v139, 0xbfb8aa3b, v139
	v_exp_f32_e32 v138, v138
	v_pk_add_f32 v[136:137], v[136:137], 1.0 op_sel_hi:[1,0]
	v_exp_f32_e32 v139, v139
	s_nop 0
	s_nop 0
	v_pk_add_f32 v[138:139], v[138:139], 1.0 op_sel_hi:[1,0]
	s_nop 0
	s_nop 0
	s_nop 0
	s_nop 0
	s_nop 0
	s_nop 0
	s_nop 0
	s_nop 0
	v_rcp_f32_e32 v137, v137
	s_nop 0
	s_nop 0
	s_nop 0
	s_nop 0
	s_nop 0
	s_nop 0
	s_nop 0
	s_nop 0
	s_nop 0
	s_nop 0
	s_nop 0
	v_rcp_f32_e32 v136, v136
	s_nop 0
	v_cvt_pk_bf16_f32 v136, v136, v137
	v_mul_f32_e32 v137, 0xbfb8aa3b, v142
	v_exp_f32_e32 v142, v137
	v_mul_f32_e32 v137, 0xbfb8aa3b, v143
	v_exp_f32_e32 v143, v137
	s_nop 0
	v_pk_add_f32 v[142:143], v[142:143], 1.0 op_sel_hi:[1,0]
	s_nop 0
	s_nop 0
	s_nop 0
	s_nop 0
	s_nop 0
	s_nop 0
	s_nop 0
	s_nop 0
	s_nop 0
	s_nop 0
	s_nop 0
	s_nop 0
	v_rcp_f32_e32 v137, v143
	s_nop 0
	s_nop 0
	s_nop 0
	s_nop 0
	s_nop 0
	s_nop 0
	s_nop 0
	s_nop 0
	s_nop 0
	s_nop 0
	s_nop 0
	v_rcp_f32_e32 v142, v142
	s_nop 0
	v_cvt_pk_bf16_f32 v137, v142, v137
	s_nop 0
	s_nop 0
	s_nop 0
	s_nop 0
	s_nop 0
	s_nop 0
	s_nop 0
	s_nop 0
	s_nop 0
	s_nop 0
	s_nop 0
	v_rcp_f32_e32 v139, v139
	s_nop 0
	s_nop 0
	s_nop 0
	s_nop 0
	s_nop 0
	s_nop 0
	s_nop 0
	s_nop 0
	s_nop 0
	s_nop 0
	s_nop 0
	v_rcp_f32_e32 v138, v138
	s_nop 0
	v_cvt_pk_bf16_f32 v138, v138, v139
	v_mul_f32_e32 v139, 0xbfb8aa3b, v140
	v_exp_f32_e32 v140, v139
	v_mul_f32_e32 v139, 0xbfb8aa3b, v141
	v_exp_f32_e32 v141, v139
	s_nop 0
	v_pk_add_f32 v[140:141], v[140:141], 1.0 op_sel_hi:[1,0]
	s_nop 0
	s_nop 0
	s_nop 0
	s_nop 0
	s_nop 0
	s_nop 0
	s_nop 0
	s_nop 0
	s_nop 0
	s_nop 0
	s_nop 0
	s_nop 0
	v_rcp_f32_e32 v139, v141
	s_nop 0
	s_nop 0
	s_nop 0
	s_nop 0
	s_nop 0
	s_nop 0
	s_nop 0
	s_nop 0
	s_nop 0
	s_nop 0
	s_nop 0
	v_rcp_f32_e32 v140, v140
	s_nop 0
	v_cvt_pk_bf16_f32 v139, v140, v139
	global_store_dwordx4 v[182:183], v[136:139], off offset:256
	s_nop 1
	v_lshlrev_b64 v[136:137], 6, v[160:161]
	v_lshl_add_u64 v[148:149], s[2:3], 0, v[136:137]
	global_load_dwordx4 v[136:139], v[148:149], off offset:16
	global_load_dwordx4 v[140:143], v[148:149], off offset:48
	global_load_dwordx4 v[144:147], v[148:149], off
	s_nop 0
	global_load_dwordx4 v[148:151], v[148:149], off offset:32
	s_waitcnt vmcnt(1)
	v_mov_b32_e32 v162, v144
	s_waitcnt vmcnt(0)
	v_mov_b32_e32 v163, v148
	v_mov_b32_e32 v148, v145
	v_pk_add_f32 v[144:145], v[162:163], v[148:149]
	v_mov_b32_e32 v148, v146
	v_mov_b32_e32 v149, v150
	v_mov_b32_e32 v150, v147
	v_pk_add_f32 v[146:147], v[148:149], v[150:151]
	s_nop 0
	v_pk_add_f32 v[144:145], v[144:145], v[146:147]
	v_mov_b32_e32 v146, v136
	v_mov_b32_e32 v147, v140
	v_mov_b32_e32 v140, v137
	v_pk_add_f32 v[136:137], v[146:147], v[140:141]
	v_mov_b32_e32 v140, v138
	v_mov_b32_e32 v141, v142
	v_mov_b32_e32 v142, v139
	v_pk_add_f32 v[138:139], v[140:141], v[142:143]
	s_nop 0
	v_pk_add_f32 v[136:137], v[136:137], v[138:139]
	s_nop 0
	v_pk_add_f32 v[136:137], v[144:145], v[136:137]
	s_nop 0
	v_add_f32_e32 v136, v136, v137
	v_fmamk_f32 v136, v136, 0x3a800000, v208
	v_cmp_gt_f32_e32 vcc, s51, v136
	v_mul_f32_e32 v137, 0x4b800000, v136
	s_nop 0
	v_cndmask_b32_e32 v136, v136, v137, vcc
	v_rsq_f32_e32 v136, v136
	s_nop 0
	v_mul_f32_e32 v137, 0x45800000, v136
	v_cndmask_b32_e32 v138, v136, v137, vcc
	v_pk_fma_f32 v[140:141], v[132:133], v[138:139], v[44:45] op_sel_hi:[1,0,1]
	v_pk_fma_f32 v[132:133], v[130:131], v[138:139], v[42:43] op_sel_hi:[1,0,1]
	v_pk_fma_f32 v[130:131], v[128:129], v[138:139], v[40:41] op_sel_hi:[1,0,1]
	v_mul_f32_e32 v128, 0xbfb8aa3b, v140
	v_mul_f32_e32 v129, 0xbfb8aa3b, v141
	v_exp_f32_e32 v128, v128
	v_exp_f32_e32 v129, v129
	v_pk_fma_f32 v[134:135], v[134:135], v[138:139], v[46:47] op_sel_hi:[1,0,1]
	v_mul_f32_e32 v130, 0xbfb8aa3b, v130
	v_mul_f32_e32 v131, 0xbfb8aa3b, v131
	v_pk_add_f32 v[128:129], v[128:129], 1.0 op_sel_hi:[1,0]
	v_exp_f32_e32 v130, v130
	s_nop 0
	s_nop 0
	v_exp_f32_e32 v131, v131
	v_lshlrev_b64 v[136:137], 11, v[160:161]
	v_lshl_add_u64 v[136:137], v[178:179], 0, v[136:137]
	s_nop 0
	s_nop 0
	s_nop 0
	s_nop 0
	s_nop 0
	s_nop 0
	s_nop 0
	s_nop 0
	v_rcp_f32_e32 v129, v129
	s_nop 0
	s_nop 0
	v_pk_add_f32 v[130:131], v[130:131], 1.0 op_sel_hi:[1,0]
	s_nop 0
	s_nop 0
	s_nop 0
	s_nop 0
	s_nop 0
	s_nop 0
	s_nop 0
	s_nop 0
	v_rcp_f32_e32 v128, v128
	s_nop 0
	v_cvt_pk_bf16_f32 v128, v128, v129
	v_mul_f32_e32 v129, 0xbfb8aa3b, v134
	v_exp_f32_e32 v134, v129
	v_mul_f32_e32 v129, 0xbfb8aa3b, v135
	v_exp_f32_e32 v135, v129
	s_nop 0
	v_pk_add_f32 v[134:135], v[134:135], 1.0 op_sel_hi:[1,0]
	s_nop 0
	s_nop 0
	s_nop 0
	s_nop 0
	s_nop 0
	s_nop 0
	s_nop 0
	s_nop 0
	s_nop 0
	s_nop 0
	s_nop 0
	s_nop 0
	v_rcp_f32_e32 v129, v135
	s_nop 0
	s_nop 0
	s_nop 0
	s_nop 0
	s_nop 0
	s_nop 0
	s_nop 0
	s_nop 0
	s_nop 0
	s_nop 0
	s_nop 0
	v_rcp_f32_e32 v134, v134
	s_nop 0
	v_cvt_pk_bf16_f32 v129, v134, v129
	s_nop 0
	s_nop 0
	s_nop 0
	s_nop 0
	s_nop 0
	s_nop 0
	s_nop 0
	s_nop 0
	s_nop 0
	s_nop 0
	s_nop 0
	v_rcp_f32_e32 v131, v131
	s_nop 0
	s_nop 0
	s_nop 0
	s_nop 0
	s_nop 0
	s_nop 0
	s_nop 0
	s_nop 0
	s_nop 0
	s_nop 0
	s_nop 0
	v_rcp_f32_e32 v130, v130
	s_nop 0
	v_cvt_pk_bf16_f32 v130, v130, v131
	v_mul_f32_e32 v131, 0xbfb8aa3b, v132
	v_exp_f32_e32 v132, v131
	v_mul_f32_e32 v131, 0xbfb8aa3b, v133
	v_exp_f32_e32 v133, v131
	s_nop 0
	v_pk_add_f32 v[132:133], v[132:133], 1.0 op_sel_hi:[1,0]
	s_nop 0
	s_nop 0
	s_nop 0
	s_nop 0
	s_nop 0
	s_nop 0
	s_nop 0
	s_nop 0
	s_nop 0
	s_nop 0
	s_nop 0
	s_nop 0
	v_rcp_f32_e32 v131, v133
	s_nop 0
	s_nop 0
	s_nop 0
	s_nop 0
	s_nop 0
	s_nop 0
	s_nop 0
	s_nop 0
	s_nop 0
	s_nop 0
	s_nop 0
	v_rcp_f32_e32 v132, v132
	s_nop 0
	v_cvt_pk_bf16_f32 v131, v132, v131
	global_store_dwordx4 v[136:137], v[128:131], off
	v_pk_fma_f32 v[126:127], v[126:127], v[138:139], v[30:31] op_sel_hi:[1,0,1]
	s_nop 0
	v_pk_fma_f32 v[128:129], v[124:125], v[138:139], v[28:29] op_sel_hi:[1,0,1]
	v_pk_fma_f32 v[124:125], v[122:123], v[138:139], v[26:27] op_sel_hi:[1,0,1]
	v_pk_fma_f32 v[122:123], v[120:121], v[138:139], v[24:25] op_sel_hi:[1,0,1]
	v_mul_f32_e32 v120, 0xbfb8aa3b, v128
	v_mul_f32_e32 v121, 0xbfb8aa3b, v129
	v_exp_f32_e32 v120, v120
	v_exp_f32_e32 v121, v121
	v_mul_f32_e32 v122, 0xbfb8aa3b, v122
	v_mul_f32_e32 v123, 0xbfb8aa3b, v123
	v_exp_f32_e32 v122, v122
	v_pk_add_f32 v[120:121], v[120:121], 1.0 op_sel_hi:[1,0]
	v_exp_f32_e32 v123, v123
	s_nop 0
	s_nop 0
	v_pk_add_f32 v[122:123], v[122:123], 1.0 op_sel_hi:[1,0]
	s_nop 0
	s_nop 0
	s_nop 0
	s_nop 0
	s_nop 0
	s_nop 0
	s_nop 0
	s_nop 0
	v_rcp_f32_e32 v121, v121
	s_nop 0
	s_nop 0
	s_nop 0
	s_nop 0
	s_nop 0
	s_nop 0
	s_nop 0
	s_nop 0
	s_nop 0
	s_nop 0
	s_nop 0
	v_rcp_f32_e32 v120, v120
	s_nop 0
	v_cvt_pk_bf16_f32 v120, v120, v121
	v_mul_f32_e32 v121, 0xbfb8aa3b, v126
	v_exp_f32_e32 v126, v121
	v_mul_f32_e32 v121, 0xbfb8aa3b, v127
	v_exp_f32_e32 v127, v121
	s_nop 0
	v_pk_add_f32 v[126:127], v[126:127], 1.0 op_sel_hi:[1,0]
	s_nop 0
	s_nop 0
	s_nop 0
	s_nop 0
	s_nop 0
	s_nop 0
	s_nop 0
	s_nop 0
	s_nop 0
	s_nop 0
	s_nop 0
	s_nop 0
	v_rcp_f32_e32 v121, v127
	s_nop 0
	s_nop 0
	s_nop 0
	s_nop 0
	s_nop 0
	s_nop 0
	s_nop 0
	s_nop 0
	s_nop 0
	s_nop 0
	s_nop 0
	v_rcp_f32_e32 v126, v126
	s_nop 0
	v_cvt_pk_bf16_f32 v121, v126, v121
	s_nop 0
	s_nop 0
	s_nop 0
	s_nop 0
	s_nop 0
	s_nop 0
	s_nop 0
	s_nop 0
	s_nop 0
	s_nop 0
	s_nop 0
	v_rcp_f32_e32 v123, v123
	s_nop 0
	s_nop 0
	s_nop 0
	s_nop 0
	s_nop 0
	s_nop 0
	s_nop 0
	s_nop 0
	s_nop 0
	s_nop 0
	s_nop 0
	v_rcp_f32_e32 v122, v122
	s_nop 0
	v_cvt_pk_bf16_f32 v122, v122, v123
	v_mul_f32_e32 v123, 0xbfb8aa3b, v124
	v_exp_f32_e32 v124, v123
	v_mul_f32_e32 v123, 0xbfb8aa3b, v125
	v_exp_f32_e32 v125, v123
	s_nop 0
	v_pk_add_f32 v[124:125], v[124:125], 1.0 op_sel_hi:[1,0]
	s_nop 0
	s_nop 0
	s_nop 0
	s_nop 0
	s_nop 0
	s_nop 0
	s_nop 0
	s_nop 0
	s_nop 0
	s_nop 0
	s_nop 0
	s_nop 0
	v_rcp_f32_e32 v123, v125
	s_nop 0
	s_nop 0
	s_nop 0
	s_nop 0
	s_nop 0
	s_nop 0
	s_nop 0
	s_nop 0
	s_nop 0
	s_nop 0
	s_nop 0
	v_rcp_f32_e32 v124, v124
	s_nop 0
	v_cvt_pk_bf16_f32 v123, v124, v123
	global_store_dwordx4 v[136:137], v[120:123], off offset:256
	v_add_u32_e32 v136, 32, v180
	v_ashrrev_i32_e32 v137, 31, v136
	v_lshlrev_b64 v[120:121], 6, v[136:137]
	v_lshl_add_u64 v[132:133], s[2:3], 0, v[120:121]
	global_load_dwordx4 v[120:123], v[132:133], off offset:16
	global_load_dwordx4 v[124:127], v[132:133], off offset:48
	global_load_dwordx4 v[128:131], v[132:133], off
	s_nop 0
	global_load_dwordx4 v[132:135], v[132:133], off offset:32
	s_waitcnt vmcnt(1)
	v_mov_b32_e32 v138, v128
	s_waitcnt vmcnt(0)
	v_mov_b32_e32 v139, v132
	v_mov_b32_e32 v132, v129
	v_pk_add_f32 v[128:129], v[138:139], v[132:133]
	v_mov_b32_e32 v132, v130
	v_mov_b32_e32 v133, v134
	v_mov_b32_e32 v134, v131
	v_pk_add_f32 v[130:131], v[132:133], v[134:135]
	s_nop 0
	v_pk_add_f32 v[128:129], v[128:129], v[130:131]
	v_mov_b32_e32 v130, v120
	v_mov_b32_e32 v131, v124
	v_mov_b32_e32 v124, v121
	v_pk_add_f32 v[120:121], v[130:131], v[124:125]
	v_mov_b32_e32 v124, v122
	v_mov_b32_e32 v125, v126
	v_mov_b32_e32 v126, v123
	v_pk_add_f32 v[122:123], v[124:125], v[126:127]
	s_nop 0
	v_pk_add_f32 v[120:121], v[120:121], v[122:123]
	s_nop 0
	v_pk_add_f32 v[120:121], v[128:129], v[120:121]
	s_nop 0
	v_add_f32_e32 v120, v120, v121
	v_fmamk_f32 v120, v120, 0x3a800000, v208
	v_cmp_gt_f32_e32 vcc, s51, v120
	v_mul_f32_e32 v121, 0x4b800000, v120
	s_nop 0
	v_cndmask_b32_e32 v120, v120, v121, vcc
	v_rsq_f32_e32 v120, v120
	s_nop 0
	v_mul_f32_e32 v121, 0x45800000, v120
	v_cndmask_b32_e32 v122, v120, v121, vcc
	v_pk_fma_f32 v[124:125], v[116:117], v[122:123], v[44:45] op_sel_hi:[1,0,1]
	v_pk_fma_f32 v[116:117], v[114:115], v[122:123], v[42:43] op_sel_hi:[1,0,1]
	v_pk_fma_f32 v[114:115], v[112:113], v[122:123], v[40:41] op_sel_hi:[1,0,1]
	v_mul_f32_e32 v112, 0xbfb8aa3b, v124
	v_mul_f32_e32 v113, 0xbfb8aa3b, v125
	v_exp_f32_e32 v112, v112
	v_exp_f32_e32 v113, v113
	v_pk_fma_f32 v[118:119], v[118:119], v[122:123], v[46:47] op_sel_hi:[1,0,1]
	v_mul_f32_e32 v114, 0xbfb8aa3b, v114
	v_mul_f32_e32 v115, 0xbfb8aa3b, v115
	v_pk_add_f32 v[112:113], v[112:113], 1.0 op_sel_hi:[1,0]
	v_exp_f32_e32 v114, v114
	s_nop 0
	s_nop 0
	v_exp_f32_e32 v115, v115
	v_lshlrev_b64 v[120:121], 11, v[136:137]
	v_lshl_add_u64 v[120:121], v[178:179], 0, v[120:121]
	s_nop 0
	s_nop 0
	s_nop 0
	s_nop 0
	s_nop 0
	s_nop 0
	s_nop 0
	s_nop 0
	v_rcp_f32_e32 v113, v113
	s_nop 0
	s_nop 0
	v_pk_add_f32 v[114:115], v[114:115], 1.0 op_sel_hi:[1,0]
	s_nop 0
	s_nop 0
	s_nop 0
	s_nop 0
	s_nop 0
	s_nop 0
	s_nop 0
	s_nop 0
	v_rcp_f32_e32 v112, v112
	s_nop 0
	v_cvt_pk_bf16_f32 v112, v112, v113
	v_mul_f32_e32 v113, 0xbfb8aa3b, v118
	v_exp_f32_e32 v118, v113
	v_mul_f32_e32 v113, 0xbfb8aa3b, v119
	v_exp_f32_e32 v119, v113
	s_nop 0
	v_pk_add_f32 v[118:119], v[118:119], 1.0 op_sel_hi:[1,0]
	s_nop 0
	s_nop 0
	s_nop 0
	s_nop 0
	s_nop 0
	s_nop 0
	s_nop 0
	s_nop 0
	s_nop 0
	s_nop 0
	s_nop 0
	s_nop 0
	v_rcp_f32_e32 v113, v119
	s_nop 0
	s_nop 0
	s_nop 0
	s_nop 0
	s_nop 0
	s_nop 0
	s_nop 0
	s_nop 0
	s_nop 0
	s_nop 0
	s_nop 0
	v_rcp_f32_e32 v118, v118
	s_nop 0
	v_cvt_pk_bf16_f32 v113, v118, v113
	s_nop 0
	s_nop 0
	s_nop 0
	s_nop 0
	s_nop 0
	s_nop 0
	s_nop 0
	s_nop 0
	s_nop 0
	s_nop 0
	s_nop 0
	v_rcp_f32_e32 v115, v115
	s_nop 0
	s_nop 0
	s_nop 0
	s_nop 0
	s_nop 0
	s_nop 0
	s_nop 0
	s_nop 0
	s_nop 0
	s_nop 0
	s_nop 0
	v_rcp_f32_e32 v114, v114
	s_nop 0
	v_cvt_pk_bf16_f32 v114, v114, v115
	v_mul_f32_e32 v115, 0xbfb8aa3b, v116
	v_exp_f32_e32 v116, v115
	v_mul_f32_e32 v115, 0xbfb8aa3b, v117
	v_exp_f32_e32 v117, v115
	s_nop 0
	v_pk_add_f32 v[116:117], v[116:117], 1.0 op_sel_hi:[1,0]
	s_nop 0
	s_nop 0
	s_nop 0
	s_nop 0
	s_nop 0
	s_nop 0
	s_nop 0
	s_nop 0
	s_nop 0
	s_nop 0
	s_nop 0
	s_nop 0
	v_rcp_f32_e32 v115, v117
	s_nop 0
	s_nop 0
	s_nop 0
	s_nop 0
	s_nop 0
	s_nop 0
	s_nop 0
	s_nop 0
	s_nop 0
	s_nop 0
	s_nop 0
	v_rcp_f32_e32 v116, v116
	s_nop 0
	v_cvt_pk_bf16_f32 v115, v116, v115
	global_store_dwordx4 v[120:121], v[112:115], off
	v_pk_fma_f32 v[110:111], v[110:111], v[122:123], v[30:31] op_sel_hi:[1,0,1]
	s_nop 0
	v_pk_fma_f32 v[112:113], v[108:109], v[122:123], v[28:29] op_sel_hi:[1,0,1]
	v_pk_fma_f32 v[108:109], v[106:107], v[122:123], v[26:27] op_sel_hi:[1,0,1]
	v_pk_fma_f32 v[106:107], v[104:105], v[122:123], v[24:25] op_sel_hi:[1,0,1]
	v_mul_f32_e32 v104, 0xbfb8aa3b, v112
	v_mul_f32_e32 v105, 0xbfb8aa3b, v113
	v_exp_f32_e32 v104, v104
	v_exp_f32_e32 v105, v105
	v_mul_f32_e32 v106, 0xbfb8aa3b, v106
	v_mul_f32_e32 v107, 0xbfb8aa3b, v107
	v_exp_f32_e32 v106, v106
	v_pk_add_f32 v[104:105], v[104:105], 1.0 op_sel_hi:[1,0]
	v_exp_f32_e32 v107, v107
	s_nop 0
	s_nop 0
	v_pk_add_f32 v[106:107], v[106:107], 1.0 op_sel_hi:[1,0]
	s_nop 0
	s_nop 0
	s_nop 0
	s_nop 0
	s_nop 0
	s_nop 0
	s_nop 0
	s_nop 0
	v_rcp_f32_e32 v105, v105
	s_nop 0
	s_nop 0
	s_nop 0
	s_nop 0
	s_nop 0
	s_nop 0
	s_nop 0
	s_nop 0
	s_nop 0
	s_nop 0
	s_nop 0
	v_rcp_f32_e32 v104, v104
	s_nop 0
	v_cvt_pk_bf16_f32 v104, v104, v105
	v_mul_f32_e32 v105, 0xbfb8aa3b, v110
	v_exp_f32_e32 v110, v105
	v_mul_f32_e32 v105, 0xbfb8aa3b, v111
	v_exp_f32_e32 v111, v105
	s_nop 0
	v_pk_add_f32 v[110:111], v[110:111], 1.0 op_sel_hi:[1,0]
	s_nop 0
	s_nop 0
	s_nop 0
	s_nop 0
	s_nop 0
	s_nop 0
	s_nop 0
	s_nop 0
	s_nop 0
	s_nop 0
	s_nop 0
	s_nop 0
	v_rcp_f32_e32 v105, v111
	s_nop 0
	s_nop 0
	s_nop 0
	s_nop 0
	s_nop 0
	s_nop 0
	s_nop 0
	s_nop 0
	s_nop 0
	s_nop 0
	s_nop 0
	v_rcp_f32_e32 v110, v110
	s_nop 0
	v_cvt_pk_bf16_f32 v105, v110, v105
	s_nop 0
	s_nop 0
	s_nop 0
	s_nop 0
	s_nop 0
	s_nop 0
	s_nop 0
	s_nop 0
	s_nop 0
	s_nop 0
	s_nop 0
	v_rcp_f32_e32 v107, v107
	s_nop 0
	s_nop 0
	s_nop 0
	s_nop 0
	s_nop 0
	s_nop 0
	s_nop 0
	s_nop 0
	s_nop 0
	s_nop 0
	s_nop 0
	v_rcp_f32_e32 v106, v106
	s_nop 0
	v_cvt_pk_bf16_f32 v106, v106, v107
	v_mul_f32_e32 v107, 0xbfb8aa3b, v108
	v_exp_f32_e32 v108, v107
	v_mul_f32_e32 v107, 0xbfb8aa3b, v109
	v_exp_f32_e32 v109, v107
	s_nop 0
	v_pk_add_f32 v[108:109], v[108:109], 1.0 op_sel_hi:[1,0]
	s_nop 0
	s_nop 0
	s_nop 0
	s_nop 0
	s_nop 0
	s_nop 0
	s_nop 0
	s_nop 0
	s_nop 0
	s_nop 0
	s_nop 0
	s_nop 0
	v_rcp_f32_e32 v107, v109
	s_nop 0
	s_nop 0
	s_nop 0
	s_nop 0
	s_nop 0
	s_nop 0
	s_nop 0
	s_nop 0
	s_nop 0
	s_nop 0
	s_nop 0
	v_rcp_f32_e32 v108, v108
	s_nop 0
	v_cvt_pk_bf16_f32 v107, v108, v107
	global_store_dwordx4 v[120:121], v[104:107], off offset:256
	v_add_u32_e32 v120, 48, v180
	v_ashrrev_i32_e32 v121, 31, v120
	v_lshlrev_b64 v[104:105], 6, v[120:121]
	v_lshl_add_u64 v[116:117], s[2:3], 0, v[104:105]
	global_load_dwordx4 v[104:107], v[116:117], off offset:16
	global_load_dwordx4 v[108:111], v[116:117], off offset:48
	global_load_dwordx4 v[112:115], v[116:117], off
	s_nop 0
	global_load_dwordx4 v[116:119], v[116:117], off offset:32
	s_waitcnt vmcnt(1)
	v_mov_b32_e32 v122, v112
	s_waitcnt vmcnt(0)
	v_mov_b32_e32 v123, v116
	v_mov_b32_e32 v116, v113
	v_pk_add_f32 v[112:113], v[122:123], v[116:117]
	v_mov_b32_e32 v116, v114
	v_mov_b32_e32 v117, v118
	v_mov_b32_e32 v118, v115
	v_pk_add_f32 v[114:115], v[116:117], v[118:119]
	s_nop 0
	v_pk_add_f32 v[112:113], v[112:113], v[114:115]
	v_mov_b32_e32 v114, v104
	v_mov_b32_e32 v115, v108
	v_mov_b32_e32 v108, v105
	v_pk_add_f32 v[104:105], v[114:115], v[108:109]
	v_mov_b32_e32 v108, v106
	v_mov_b32_e32 v109, v110
	v_mov_b32_e32 v110, v107
	v_pk_add_f32 v[106:107], v[108:109], v[110:111]
	s_nop 0
	v_pk_add_f32 v[104:105], v[104:105], v[106:107]
	s_nop 0
	v_pk_add_f32 v[104:105], v[112:113], v[104:105]
	s_nop 0
	v_add_f32_e32 v104, v104, v105
	v_fmamk_f32 v104, v104, 0x3a800000, v208
	v_cmp_gt_f32_e32 vcc, s51, v104
	v_mul_f32_e32 v105, 0x4b800000, v104
	s_nop 0
	v_cndmask_b32_e32 v104, v104, v105, vcc
	v_rsq_f32_e32 v104, v104
	s_nop 0
	v_mul_f32_e32 v105, 0x45800000, v104
	v_cndmask_b32_e32 v106, v104, v105, vcc
	v_pk_fma_f32 v[108:109], v[100:101], v[106:107], v[44:45] op_sel_hi:[1,0,1]
	v_pk_fma_f32 v[100:101], v[98:99], v[106:107], v[42:43] op_sel_hi:[1,0,1]
	v_pk_fma_f32 v[98:99], v[96:97], v[106:107], v[40:41] op_sel_hi:[1,0,1]
	v_mul_f32_e32 v96, 0xbfb8aa3b, v108
	v_mul_f32_e32 v97, 0xbfb8aa3b, v109
	v_exp_f32_e32 v96, v96
	v_exp_f32_e32 v97, v97
	v_pk_fma_f32 v[102:103], v[102:103], v[106:107], v[46:47] op_sel_hi:[1,0,1]
	v_mul_f32_e32 v98, 0xbfb8aa3b, v98
	v_mul_f32_e32 v99, 0xbfb8aa3b, v99
	v_pk_add_f32 v[96:97], v[96:97], 1.0 op_sel_hi:[1,0]
	v_exp_f32_e32 v98, v98
	s_nop 0
	s_nop 0
	v_exp_f32_e32 v99, v99
	v_lshlrev_b64 v[104:105], 11, v[120:121]
	v_lshl_add_u64 v[104:105], v[178:179], 0, v[104:105]
	s_nop 0
	s_nop 0
	s_nop 0
	s_nop 0
	s_nop 0
	s_nop 0
	s_nop 0
	s_nop 0
	v_rcp_f32_e32 v97, v97
	s_nop 0
	s_nop 0
	v_pk_add_f32 v[98:99], v[98:99], 1.0 op_sel_hi:[1,0]
	s_nop 0
	s_nop 0
	s_nop 0
	s_nop 0
	s_nop 0
	s_nop 0
	s_nop 0
	s_nop 0
	v_rcp_f32_e32 v96, v96
	s_nop 0
	v_cvt_pk_bf16_f32 v96, v96, v97
	v_mul_f32_e32 v97, 0xbfb8aa3b, v102
	v_exp_f32_e32 v102, v97
	v_mul_f32_e32 v97, 0xbfb8aa3b, v103
	v_exp_f32_e32 v103, v97
	s_nop 0
	v_pk_add_f32 v[102:103], v[102:103], 1.0 op_sel_hi:[1,0]
	s_nop 0
	s_nop 0
	s_nop 0
	s_nop 0
	s_nop 0
	s_nop 0
	s_nop 0
	s_nop 0
	s_nop 0
	s_nop 0
	s_nop 0
	s_nop 0
	v_rcp_f32_e32 v97, v103
	s_nop 0
	s_nop 0
	s_nop 0
	s_nop 0
	s_nop 0
	s_nop 0
	s_nop 0
	s_nop 0
	s_nop 0
	s_nop 0
	s_nop 0
	v_rcp_f32_e32 v102, v102
	s_nop 0
	v_cvt_pk_bf16_f32 v97, v102, v97
	s_nop 0
	s_nop 0
	s_nop 0
	s_nop 0
	s_nop 0
	s_nop 0
	s_nop 0
	s_nop 0
	s_nop 0
	s_nop 0
	s_nop 0
	v_rcp_f32_e32 v99, v99
	s_nop 0
	s_nop 0
	s_nop 0
	s_nop 0
	s_nop 0
	s_nop 0
	s_nop 0
	s_nop 0
	s_nop 0
	s_nop 0
	s_nop 0
	v_rcp_f32_e32 v98, v98
	s_nop 0
	v_cvt_pk_bf16_f32 v98, v98, v99
	v_mul_f32_e32 v99, 0xbfb8aa3b, v100
	v_exp_f32_e32 v100, v99
	v_mul_f32_e32 v99, 0xbfb8aa3b, v101
	v_exp_f32_e32 v101, v99
	s_nop 0
	v_pk_add_f32 v[100:101], v[100:101], 1.0 op_sel_hi:[1,0]
	s_nop 0
	s_nop 0
	s_nop 0
	s_nop 0
	s_nop 0
	s_nop 0
	s_nop 0
	s_nop 0
	s_nop 0
	s_nop 0
	s_nop 0
	s_nop 0
	v_rcp_f32_e32 v99, v101
	s_nop 0
	s_nop 0
	s_nop 0
	s_nop 0
	s_nop 0
	s_nop 0
	s_nop 0
	s_nop 0
	s_nop 0
	s_nop 0
	s_nop 0
	v_rcp_f32_e32 v100, v100
	s_nop 0
	v_cvt_pk_bf16_f32 v99, v100, v99
	global_store_dwordx4 v[104:105], v[96:99], off
	v_pk_fma_f32 v[94:95], v[94:95], v[106:107], v[30:31] op_sel_hi:[1,0,1]
	s_nop 0
	v_pk_fma_f32 v[96:97], v[92:93], v[106:107], v[28:29] op_sel_hi:[1,0,1]
	v_pk_fma_f32 v[92:93], v[90:91], v[106:107], v[26:27] op_sel_hi:[1,0,1]
	v_pk_fma_f32 v[90:91], v[88:89], v[106:107], v[24:25] op_sel_hi:[1,0,1]
	v_mul_f32_e32 v88, 0xbfb8aa3b, v96
	v_mul_f32_e32 v89, 0xbfb8aa3b, v97
	v_exp_f32_e32 v88, v88
	v_exp_f32_e32 v89, v89
	v_mul_f32_e32 v90, 0xbfb8aa3b, v90
	v_mul_f32_e32 v91, 0xbfb8aa3b, v91
	v_exp_f32_e32 v90, v90
	v_pk_add_f32 v[88:89], v[88:89], 1.0 op_sel_hi:[1,0]
	v_exp_f32_e32 v91, v91
	s_nop 0
	s_nop 0
	v_pk_add_f32 v[90:91], v[90:91], 1.0 op_sel_hi:[1,0]
	s_nop 0
	s_nop 0
	s_nop 0
	s_nop 0
	s_nop 0
	s_nop 0
	s_nop 0
	s_nop 0
	v_rcp_f32_e32 v89, v89
	s_nop 0
	s_nop 0
	s_nop 0
	s_nop 0
	s_nop 0
	s_nop 0
	s_nop 0
	s_nop 0
	s_nop 0
	s_nop 0
	s_nop 0
	v_rcp_f32_e32 v88, v88
	s_nop 0
	v_cvt_pk_bf16_f32 v88, v88, v89
	v_mul_f32_e32 v89, 0xbfb8aa3b, v94
	v_exp_f32_e32 v94, v89
	v_mul_f32_e32 v89, 0xbfb8aa3b, v95
	v_exp_f32_e32 v95, v89
	s_nop 0
	v_pk_add_f32 v[94:95], v[94:95], 1.0 op_sel_hi:[1,0]
	s_nop 0
	s_nop 0
	s_nop 0
	s_nop 0
	s_nop 0
	s_nop 0
	s_nop 0
	s_nop 0
	s_nop 0
	s_nop 0
	s_nop 0
	s_nop 0
	v_rcp_f32_e32 v89, v95
	s_nop 0
	s_nop 0
	s_nop 0
	s_nop 0
	s_nop 0
	s_nop 0
	s_nop 0
	s_nop 0
	s_nop 0
	s_nop 0
	s_nop 0
	v_rcp_f32_e32 v94, v94
	s_nop 0
	v_cvt_pk_bf16_f32 v89, v94, v89
	s_nop 0
	s_nop 0
	s_nop 0
	s_nop 0
	s_nop 0
	s_nop 0
	s_nop 0
	s_nop 0
	s_nop 0
	s_nop 0
	s_nop 0
	v_rcp_f32_e32 v91, v91
	s_nop 0
	s_nop 0
	s_nop 0
	s_nop 0
	s_nop 0
	s_nop 0
	s_nop 0
	s_nop 0
	s_nop 0
	s_nop 0
	s_nop 0
	v_rcp_f32_e32 v90, v90
	s_nop 0
	v_cvt_pk_bf16_f32 v90, v90, v91
	v_mul_f32_e32 v91, 0xbfb8aa3b, v92
	v_exp_f32_e32 v92, v91
	v_mul_f32_e32 v91, 0xbfb8aa3b, v93
	v_exp_f32_e32 v93, v91
	s_nop 0
	v_pk_add_f32 v[92:93], v[92:93], 1.0 op_sel_hi:[1,0]
	s_nop 0
	s_nop 0
	s_nop 0
	s_nop 0
	s_nop 0
	s_nop 0
	s_nop 0
	s_nop 0
	s_nop 0
	s_nop 0
	s_nop 0
	s_nop 0
	v_rcp_f32_e32 v91, v93
	s_nop 0
	s_nop 0
	s_nop 0
	s_nop 0
	s_nop 0
	s_nop 0
	s_nop 0
	s_nop 0
	s_nop 0
	s_nop 0
	s_nop 0
	v_rcp_f32_e32 v92, v92
	s_nop 0
	v_cvt_pk_bf16_f32 v91, v92, v91
	global_store_dwordx4 v[104:105], v[88:91], off offset:256
	v_add_u32_e32 v104, 0x80, v180
	v_ashrrev_i32_e32 v105, 31, v104
	v_lshlrev_b64 v[88:89], 6, v[104:105]
	v_lshl_add_u64 v[100:101], s[2:3], 0, v[88:89]
	global_load_dwordx4 v[88:91], v[100:101], off offset:16
	global_load_dwordx4 v[92:95], v[100:101], off offset:48
	global_load_dwordx4 v[96:99], v[100:101], off
	s_nop 0
	global_load_dwordx4 v[100:103], v[100:101], off offset:32
	s_waitcnt vmcnt(1)
	v_mov_b32_e32 v106, v96
	s_waitcnt vmcnt(0)
	v_mov_b32_e32 v107, v100
	v_mov_b32_e32 v100, v97
	v_pk_add_f32 v[96:97], v[106:107], v[100:101]
	v_mov_b32_e32 v100, v98
	v_mov_b32_e32 v101, v102
	v_mov_b32_e32 v102, v99
	v_pk_add_f32 v[98:99], v[100:101], v[102:103]
	s_nop 0
	v_pk_add_f32 v[96:97], v[96:97], v[98:99]
	v_mov_b32_e32 v98, v88
	v_mov_b32_e32 v99, v92
	v_mov_b32_e32 v92, v89
	v_pk_add_f32 v[88:89], v[98:99], v[92:93]
	v_mov_b32_e32 v92, v90
	v_mov_b32_e32 v93, v94
	v_mov_b32_e32 v94, v91
	v_pk_add_f32 v[90:91], v[92:93], v[94:95]
	s_nop 0
	v_pk_add_f32 v[88:89], v[88:89], v[90:91]
	s_nop 0
	v_pk_add_f32 v[88:89], v[96:97], v[88:89]
	s_nop 0
	v_add_f32_e32 v88, v88, v89
	v_fmamk_f32 v88, v88, 0x3a800000, v208
	v_cmp_gt_f32_e32 vcc, s51, v88
	v_mul_f32_e32 v89, 0x4b800000, v88
	s_nop 0
	v_cndmask_b32_e32 v88, v88, v89, vcc
	v_rsq_f32_e32 v88, v88
	s_nop 0
	v_mul_f32_e32 v89, 0x45800000, v88
	v_cndmask_b32_e32 v90, v88, v89, vcc
	v_pk_fma_f32 v[92:93], v[84:85], v[90:91], v[44:45] op_sel_hi:[1,0,1]
	v_pk_fma_f32 v[84:85], v[82:83], v[90:91], v[42:43] op_sel_hi:[1,0,1]
	v_pk_fma_f32 v[82:83], v[80:81], v[90:91], v[40:41] op_sel_hi:[1,0,1]
	v_mul_f32_e32 v80, 0xbfb8aa3b, v92
	v_mul_f32_e32 v81, 0xbfb8aa3b, v93
	v_exp_f32_e32 v80, v80
	v_exp_f32_e32 v81, v81
	v_pk_fma_f32 v[86:87], v[86:87], v[90:91], v[46:47] op_sel_hi:[1,0,1]
	v_mul_f32_e32 v82, 0xbfb8aa3b, v82
	v_mul_f32_e32 v83, 0xbfb8aa3b, v83
	v_pk_add_f32 v[80:81], v[80:81], 1.0 op_sel_hi:[1,0]
	v_exp_f32_e32 v82, v82
	s_nop 0
	s_nop 0
	v_exp_f32_e32 v83, v83
	v_lshlrev_b64 v[88:89], 11, v[104:105]
	v_lshl_add_u64 v[88:89], v[178:179], 0, v[88:89]
	s_nop 0
	s_nop 0
	s_nop 0
	s_nop 0
	s_nop 0
	s_nop 0
	s_nop 0
	s_nop 0
	v_rcp_f32_e32 v81, v81
	s_nop 0
	s_nop 0
	v_pk_add_f32 v[82:83], v[82:83], 1.0 op_sel_hi:[1,0]
	s_nop 0
	s_nop 0
	s_nop 0
	s_nop 0
	s_nop 0
	s_nop 0
	s_nop 0
	s_nop 0
	v_rcp_f32_e32 v80, v80
	s_nop 0
	v_cvt_pk_bf16_f32 v80, v80, v81
	v_mul_f32_e32 v81, 0xbfb8aa3b, v86
	v_exp_f32_e32 v86, v81
	v_mul_f32_e32 v81, 0xbfb8aa3b, v87
	v_exp_f32_e32 v87, v81
	s_nop 0
	v_pk_add_f32 v[86:87], v[86:87], 1.0 op_sel_hi:[1,0]
	s_nop 0
	s_nop 0
	s_nop 0
	s_nop 0
	s_nop 0
	s_nop 0
	s_nop 0
	s_nop 0
	s_nop 0
	s_nop 0
	s_nop 0
	s_nop 0
	v_rcp_f32_e32 v81, v87
	s_nop 0
	s_nop 0
	s_nop 0
	s_nop 0
	s_nop 0
	s_nop 0
	s_nop 0
	s_nop 0
	s_nop 0
	s_nop 0
	s_nop 0
	v_rcp_f32_e32 v86, v86
	s_nop 0
	v_cvt_pk_bf16_f32 v81, v86, v81
	s_nop 0
	s_nop 0
	s_nop 0
	s_nop 0
	s_nop 0
	s_nop 0
	s_nop 0
	s_nop 0
	s_nop 0
	s_nop 0
	s_nop 0
	v_rcp_f32_e32 v83, v83
	s_nop 0
	s_nop 0
	s_nop 0
	s_nop 0
	s_nop 0
	s_nop 0
	s_nop 0
	s_nop 0
	s_nop 0
	s_nop 0
	s_nop 0
	v_rcp_f32_e32 v82, v82
	s_nop 0
	v_cvt_pk_bf16_f32 v82, v82, v83
	v_mul_f32_e32 v83, 0xbfb8aa3b, v84
	v_exp_f32_e32 v84, v83
	v_mul_f32_e32 v83, 0xbfb8aa3b, v85
	v_exp_f32_e32 v85, v83
	s_nop 0
	v_pk_add_f32 v[84:85], v[84:85], 1.0 op_sel_hi:[1,0]
	s_nop 0
	s_nop 0
	s_nop 0
	s_nop 0
	s_nop 0
	s_nop 0
	s_nop 0
	s_nop 0
	s_nop 0
	s_nop 0
	s_nop 0
	s_nop 0
	v_rcp_f32_e32 v83, v85
	s_nop 0
	s_nop 0
	s_nop 0
	s_nop 0
	s_nop 0
	s_nop 0
	s_nop 0
	s_nop 0
	s_nop 0
	s_nop 0
	s_nop 0
	v_rcp_f32_e32 v84, v84
	s_nop 0
	v_cvt_pk_bf16_f32 v83, v84, v83
	global_store_dwordx4 v[88:89], v[80:83], off
	v_pk_fma_f32 v[78:79], v[78:79], v[90:91], v[30:31] op_sel_hi:[1,0,1]
	s_nop 0
	v_pk_fma_f32 v[80:81], v[76:77], v[90:91], v[28:29] op_sel_hi:[1,0,1]
	v_pk_fma_f32 v[76:77], v[74:75], v[90:91], v[26:27] op_sel_hi:[1,0,1]
	v_pk_fma_f32 v[74:75], v[72:73], v[90:91], v[24:25] op_sel_hi:[1,0,1]
	v_mul_f32_e32 v72, 0xbfb8aa3b, v80
	v_mul_f32_e32 v73, 0xbfb8aa3b, v81
	v_exp_f32_e32 v72, v72
	v_exp_f32_e32 v73, v73
	v_mul_f32_e32 v74, 0xbfb8aa3b, v74
	v_mul_f32_e32 v75, 0xbfb8aa3b, v75
	v_exp_f32_e32 v74, v74
	v_pk_add_f32 v[72:73], v[72:73], 1.0 op_sel_hi:[1,0]
	v_exp_f32_e32 v75, v75
	s_nop 0
	s_nop 0
	v_pk_add_f32 v[74:75], v[74:75], 1.0 op_sel_hi:[1,0]
	s_nop 0
	s_nop 0
	s_nop 0
	s_nop 0
	s_nop 0
	s_nop 0
	s_nop 0
	s_nop 0
	v_rcp_f32_e32 v73, v73
	s_nop 0
	s_nop 0
	s_nop 0
	s_nop 0
	s_nop 0
	s_nop 0
	s_nop 0
	s_nop 0
	s_nop 0
	s_nop 0
	s_nop 0
	v_rcp_f32_e32 v72, v72
	s_nop 0
	v_cvt_pk_bf16_f32 v72, v72, v73
	v_mul_f32_e32 v73, 0xbfb8aa3b, v78
	v_exp_f32_e32 v78, v73
	v_mul_f32_e32 v73, 0xbfb8aa3b, v79
	v_exp_f32_e32 v79, v73
	s_nop 0
	v_pk_add_f32 v[78:79], v[78:79], 1.0 op_sel_hi:[1,0]
	s_nop 0
	s_nop 0
	s_nop 0
	s_nop 0
	s_nop 0
	s_nop 0
	s_nop 0
	s_nop 0
	s_nop 0
	s_nop 0
	s_nop 0
	s_nop 0
	v_rcp_f32_e32 v73, v79
	s_nop 0
	s_nop 0
	s_nop 0
	s_nop 0
	s_nop 0
	s_nop 0
	s_nop 0
	s_nop 0
	s_nop 0
	s_nop 0
	s_nop 0
	v_rcp_f32_e32 v78, v78
	s_nop 0
	v_cvt_pk_bf16_f32 v73, v78, v73
	s_nop 0
	s_nop 0
	s_nop 0
	s_nop 0
	s_nop 0
	s_nop 0
	s_nop 0
	s_nop 0
	s_nop 0
	s_nop 0
	s_nop 0
	v_rcp_f32_e32 v75, v75
	s_nop 0
	s_nop 0
	s_nop 0
	s_nop 0
	s_nop 0
	s_nop 0
	s_nop 0
	s_nop 0
	s_nop 0
	s_nop 0
	s_nop 0
	v_rcp_f32_e32 v74, v74
	s_nop 0
	v_cvt_pk_bf16_f32 v74, v74, v75
	v_mul_f32_e32 v75, 0xbfb8aa3b, v76
	v_exp_f32_e32 v76, v75
	v_mul_f32_e32 v75, 0xbfb8aa3b, v77
	v_exp_f32_e32 v77, v75
	s_nop 0
	v_pk_add_f32 v[76:77], v[76:77], 1.0 op_sel_hi:[1,0]
	s_nop 0
	s_nop 0
	s_nop 0
	s_nop 0
	s_nop 0
	s_nop 0
	s_nop 0
	s_nop 0
	s_nop 0
	s_nop 0
	s_nop 0
	s_nop 0
	v_rcp_f32_e32 v75, v77
	s_nop 0
	s_nop 0
	s_nop 0
	s_nop 0
	s_nop 0
	s_nop 0
	s_nop 0
	s_nop 0
	s_nop 0
	s_nop 0
	s_nop 0
	v_rcp_f32_e32 v76, v76
	s_nop 0
	v_cvt_pk_bf16_f32 v75, v76, v75
	global_store_dwordx4 v[88:89], v[72:75], off offset:256
	v_add_u32_e32 v88, 0x90, v180
	v_ashrrev_i32_e32 v89, 31, v88
	v_lshlrev_b64 v[72:73], 6, v[88:89]
	v_lshl_add_u64 v[84:85], s[2:3], 0, v[72:73]
	global_load_dwordx4 v[72:75], v[84:85], off offset:16
	global_load_dwordx4 v[76:79], v[84:85], off offset:48
	global_load_dwordx4 v[80:83], v[84:85], off
	s_nop 0
	global_load_dwordx4 v[84:87], v[84:85], off offset:32
	s_waitcnt vmcnt(1)
	v_mov_b32_e32 v90, v80
	s_waitcnt vmcnt(0)
	v_mov_b32_e32 v91, v84
	v_mov_b32_e32 v84, v81
	v_pk_add_f32 v[80:81], v[90:91], v[84:85]
	v_mov_b32_e32 v84, v82
	v_mov_b32_e32 v85, v86
	v_mov_b32_e32 v86, v83
	v_pk_add_f32 v[82:83], v[84:85], v[86:87]
	s_nop 0
	v_pk_add_f32 v[80:81], v[80:81], v[82:83]
	v_mov_b32_e32 v82, v72
	v_mov_b32_e32 v83, v76
	v_mov_b32_e32 v76, v73
	v_pk_add_f32 v[72:73], v[82:83], v[76:77]
	v_mov_b32_e32 v76, v74
	v_mov_b32_e32 v77, v78
	v_mov_b32_e32 v78, v75
	v_pk_add_f32 v[74:75], v[76:77], v[78:79]
	s_nop 0
	v_pk_add_f32 v[72:73], v[72:73], v[74:75]
	s_nop 0
	v_pk_add_f32 v[72:73], v[80:81], v[72:73]
	s_nop 0
	v_add_f32_e32 v72, v72, v73
	v_fmamk_f32 v72, v72, 0x3a800000, v208
	v_cmp_gt_f32_e32 vcc, s51, v72
	v_mul_f32_e32 v73, 0x4b800000, v72
	s_nop 0
	v_cndmask_b32_e32 v72, v72, v73, vcc
	v_rsq_f32_e32 v72, v72
	s_nop 0
	v_mul_f32_e32 v73, 0x45800000, v72
	v_cndmask_b32_e32 v74, v72, v73, vcc
	v_pk_fma_f32 v[76:77], v[68:69], v[74:75], v[44:45] op_sel_hi:[1,0,1]
	v_pk_fma_f32 v[68:69], v[66:67], v[74:75], v[42:43] op_sel_hi:[1,0,1]
	v_pk_fma_f32 v[66:67], v[64:65], v[74:75], v[40:41] op_sel_hi:[1,0,1]
	v_mul_f32_e32 v64, 0xbfb8aa3b, v76
	v_mul_f32_e32 v65, 0xbfb8aa3b, v77
	v_exp_f32_e32 v64, v64
	v_exp_f32_e32 v65, v65
	v_pk_fma_f32 v[70:71], v[70:71], v[74:75], v[46:47] op_sel_hi:[1,0,1]
	v_mul_f32_e32 v66, 0xbfb8aa3b, v66
	v_mul_f32_e32 v67, 0xbfb8aa3b, v67
	v_pk_add_f32 v[64:65], v[64:65], 1.0 op_sel_hi:[1,0]
	v_exp_f32_e32 v66, v66
	s_nop 0
	s_nop 0
	v_exp_f32_e32 v67, v67
	v_lshlrev_b64 v[72:73], 11, v[88:89]
	v_lshl_add_u64 v[72:73], v[178:179], 0, v[72:73]
	s_nop 0
	s_nop 0
	s_nop 0
	s_nop 0
	s_nop 0
	s_nop 0
	s_nop 0
	s_nop 0
	v_rcp_f32_e32 v65, v65
	s_nop 0
	s_nop 0
	v_pk_add_f32 v[66:67], v[66:67], 1.0 op_sel_hi:[1,0]
	s_nop 0
	s_nop 0
	s_nop 0
	s_nop 0
	s_nop 0
	s_nop 0
	s_nop 0
	s_nop 0
	v_rcp_f32_e32 v64, v64
	s_nop 0
	v_cvt_pk_bf16_f32 v64, v64, v65
	v_mul_f32_e32 v65, 0xbfb8aa3b, v70
	v_exp_f32_e32 v70, v65
	v_mul_f32_e32 v65, 0xbfb8aa3b, v71
	v_exp_f32_e32 v71, v65
	s_nop 0
	v_pk_add_f32 v[70:71], v[70:71], 1.0 op_sel_hi:[1,0]
	s_nop 0
	s_nop 0
	s_nop 0
	s_nop 0
	s_nop 0
	s_nop 0
	s_nop 0
	s_nop 0
	s_nop 0
	s_nop 0
	s_nop 0
	s_nop 0
	v_rcp_f32_e32 v65, v71
	s_nop 0
	s_nop 0
	s_nop 0
	s_nop 0
	s_nop 0
	s_nop 0
	s_nop 0
	s_nop 0
	s_nop 0
	s_nop 0
	s_nop 0
	v_rcp_f32_e32 v70, v70
	s_nop 0
	v_cvt_pk_bf16_f32 v65, v70, v65
	s_nop 0
	s_nop 0
	s_nop 0
	s_nop 0
	s_nop 0
	s_nop 0
	s_nop 0
	s_nop 0
	s_nop 0
	s_nop 0
	s_nop 0
	v_rcp_f32_e32 v67, v67
	s_nop 0
	s_nop 0
	s_nop 0
	s_nop 0
	s_nop 0
	s_nop 0
	s_nop 0
	s_nop 0
	s_nop 0
	s_nop 0
	s_nop 0
	v_rcp_f32_e32 v66, v66
	s_nop 0
	v_cvt_pk_bf16_f32 v66, v66, v67
	v_mul_f32_e32 v67, 0xbfb8aa3b, v68
	v_exp_f32_e32 v68, v67
	v_mul_f32_e32 v67, 0xbfb8aa3b, v69
	v_exp_f32_e32 v69, v67
	s_nop 0
	v_pk_add_f32 v[68:69], v[68:69], 1.0 op_sel_hi:[1,0]
	s_nop 0
	s_nop 0
	s_nop 0
	s_nop 0
	s_nop 0
	s_nop 0
	s_nop 0
	s_nop 0
	s_nop 0
	s_nop 0
	s_nop 0
	s_nop 0
	v_rcp_f32_e32 v67, v69
	s_nop 0
	s_nop 0
	s_nop 0
	s_nop 0
	s_nop 0
	s_nop 0
	s_nop 0
	s_nop 0
	s_nop 0
	s_nop 0
	s_nop 0
	v_rcp_f32_e32 v68, v68
	s_nop 0
	v_cvt_pk_bf16_f32 v67, v68, v67
	global_store_dwordx4 v[72:73], v[64:67], off
	v_pk_fma_f32 v[62:63], v[62:63], v[74:75], v[30:31] op_sel_hi:[1,0,1]
	s_nop 0
	v_pk_fma_f32 v[64:65], v[60:61], v[74:75], v[28:29] op_sel_hi:[1,0,1]
	v_pk_fma_f32 v[60:61], v[58:59], v[74:75], v[26:27] op_sel_hi:[1,0,1]
	v_pk_fma_f32 v[58:59], v[56:57], v[74:75], v[24:25] op_sel_hi:[1,0,1]
	v_mul_f32_e32 v56, 0xbfb8aa3b, v64
	v_mul_f32_e32 v57, 0xbfb8aa3b, v65
	v_exp_f32_e32 v56, v56
	v_exp_f32_e32 v57, v57
	v_mul_f32_e32 v58, 0xbfb8aa3b, v58
	v_mul_f32_e32 v59, 0xbfb8aa3b, v59
	v_exp_f32_e32 v58, v58
	v_pk_add_f32 v[56:57], v[56:57], 1.0 op_sel_hi:[1,0]
	v_exp_f32_e32 v59, v59
	s_nop 0
	s_nop 0
	v_pk_add_f32 v[58:59], v[58:59], 1.0 op_sel_hi:[1,0]
	s_nop 0
	s_nop 0
	s_nop 0
	s_nop 0
	s_nop 0
	s_nop 0
	s_nop 0
	s_nop 0
	v_rcp_f32_e32 v57, v57
	s_nop 0
	s_nop 0
	s_nop 0
	s_nop 0
	s_nop 0
	s_nop 0
	s_nop 0
	s_nop 0
	s_nop 0
	s_nop 0
	s_nop 0
	v_rcp_f32_e32 v56, v56
	s_nop 0
	v_cvt_pk_bf16_f32 v56, v56, v57
	v_mul_f32_e32 v57, 0xbfb8aa3b, v62
	v_exp_f32_e32 v62, v57
	v_mul_f32_e32 v57, 0xbfb8aa3b, v63
	v_exp_f32_e32 v63, v57
	s_nop 0
	v_pk_add_f32 v[62:63], v[62:63], 1.0 op_sel_hi:[1,0]
	s_nop 0
	s_nop 0
	s_nop 0
	s_nop 0
	s_nop 0
	s_nop 0
	s_nop 0
	s_nop 0
	s_nop 0
	s_nop 0
	s_nop 0
	s_nop 0
	v_rcp_f32_e32 v57, v63
	s_nop 0
	s_nop 0
	s_nop 0
	s_nop 0
	s_nop 0
	s_nop 0
	s_nop 0
	s_nop 0
	s_nop 0
	s_nop 0
	s_nop 0
	v_rcp_f32_e32 v62, v62
	s_nop 0
	v_cvt_pk_bf16_f32 v57, v62, v57
	s_nop 0
	s_nop 0
	s_nop 0
	s_nop 0
	s_nop 0
	s_nop 0
	s_nop 0
	s_nop 0
	s_nop 0
	s_nop 0
	s_nop 0
	v_rcp_f32_e32 v59, v59
	s_nop 0
	s_nop 0
	s_nop 0
	s_nop 0
	s_nop 0
	s_nop 0
	s_nop 0
	s_nop 0
	s_nop 0
	s_nop 0
	s_nop 0
	v_rcp_f32_e32 v58, v58
	s_nop 0
	v_cvt_pk_bf16_f32 v58, v58, v59
	v_mul_f32_e32 v59, 0xbfb8aa3b, v60
	v_exp_f32_e32 v60, v59
	v_mul_f32_e32 v59, 0xbfb8aa3b, v61
	v_exp_f32_e32 v61, v59
	s_nop 0
	v_pk_add_f32 v[60:61], v[60:61], 1.0 op_sel_hi:[1,0]
	s_nop 0
	s_nop 0
	s_nop 0
	s_nop 0
	s_nop 0
	s_nop 0
	s_nop 0
	s_nop 0
	s_nop 0
	s_nop 0
	s_nop 0
	s_nop 0
	v_rcp_f32_e32 v59, v61
	s_nop 0
	s_nop 0
	s_nop 0
	s_nop 0
	s_nop 0
	s_nop 0
	s_nop 0
	s_nop 0
	s_nop 0
	s_nop 0
	s_nop 0
	v_rcp_f32_e32 v60, v60
	s_nop 0
	v_cvt_pk_bf16_f32 v59, v60, v59
	global_store_dwordx4 v[72:73], v[56:59], off offset:256
	v_add_u32_e32 v72, 0xa0, v180
	v_ashrrev_i32_e32 v73, 31, v72
	v_lshlrev_b64 v[56:57], 6, v[72:73]
	v_lshl_add_u64 v[68:69], s[2:3], 0, v[56:57]
	global_load_dwordx4 v[56:59], v[68:69], off offset:16
	global_load_dwordx4 v[60:63], v[68:69], off offset:48
	global_load_dwordx4 v[64:67], v[68:69], off
	s_nop 0
	global_load_dwordx4 v[68:71], v[68:69], off offset:32
	s_waitcnt vmcnt(1)
	v_mov_b32_e32 v74, v64
	s_waitcnt vmcnt(0)
	v_mov_b32_e32 v75, v68
	v_mov_b32_e32 v68, v65
	v_pk_add_f32 v[64:65], v[74:75], v[68:69]
	v_mov_b32_e32 v68, v66
	v_mov_b32_e32 v69, v70
	v_mov_b32_e32 v70, v67
	v_pk_add_f32 v[66:67], v[68:69], v[70:71]
	s_nop 0
	v_pk_add_f32 v[64:65], v[64:65], v[66:67]
	v_mov_b32_e32 v66, v56
	v_mov_b32_e32 v67, v60
	v_mov_b32_e32 v60, v57
	v_pk_add_f32 v[56:57], v[66:67], v[60:61]
	v_mov_b32_e32 v60, v58
	v_mov_b32_e32 v61, v62
	v_mov_b32_e32 v62, v59
	v_pk_add_f32 v[58:59], v[60:61], v[62:63]
	s_nop 0
	v_pk_add_f32 v[56:57], v[56:57], v[58:59]
	s_nop 0
	v_pk_add_f32 v[56:57], v[64:65], v[56:57]
	s_nop 0
	v_add_f32_e32 v56, v56, v57
	v_fmamk_f32 v56, v56, 0x3a800000, v208
	v_cmp_gt_f32_e32 vcc, s51, v56
	v_mul_f32_e32 v57, 0x4b800000, v56
	s_nop 0
	v_cndmask_b32_e32 v56, v56, v57, vcc
	v_rsq_f32_e32 v56, v56
	s_nop 0
	v_mul_f32_e32 v57, 0x45800000, v56
	v_cndmask_b32_e32 v58, v56, v57, vcc
	v_pk_fma_f32 v[60:61], v[52:53], v[58:59], v[44:45] op_sel_hi:[1,0,1]
	v_pk_fma_f32 v[52:53], v[50:51], v[58:59], v[42:43] op_sel_hi:[1,0,1]
	v_pk_fma_f32 v[50:51], v[48:49], v[58:59], v[40:41] op_sel_hi:[1,0,1]
	v_mul_f32_e32 v48, 0xbfb8aa3b, v60
	v_mul_f32_e32 v49, 0xbfb8aa3b, v61
	v_exp_f32_e32 v48, v48
	v_exp_f32_e32 v49, v49
	v_pk_fma_f32 v[54:55], v[54:55], v[58:59], v[46:47] op_sel_hi:[1,0,1]
	v_mul_f32_e32 v50, 0xbfb8aa3b, v50
	v_mul_f32_e32 v51, 0xbfb8aa3b, v51
	v_pk_add_f32 v[48:49], v[48:49], 1.0 op_sel_hi:[1,0]
	v_exp_f32_e32 v50, v50
	s_nop 0
	s_nop 0
	v_exp_f32_e32 v51, v51
	v_lshlrev_b64 v[56:57], 11, v[72:73]
	v_lshl_add_u64 v[56:57], v[178:179], 0, v[56:57]
	s_nop 0
	s_nop 0
	s_nop 0
	s_nop 0
	s_nop 0
	s_nop 0
	s_nop 0
	s_nop 0
	v_rcp_f32_e32 v49, v49
	s_nop 0
	s_nop 0
	v_pk_add_f32 v[50:51], v[50:51], 1.0 op_sel_hi:[1,0]
	s_nop 0
	s_nop 0
	s_nop 0
	s_nop 0
	s_nop 0
	s_nop 0
	s_nop 0
	s_nop 0
	v_rcp_f32_e32 v48, v48
	s_nop 0
	v_cvt_pk_bf16_f32 v48, v48, v49
	v_mul_f32_e32 v49, 0xbfb8aa3b, v54
	v_exp_f32_e32 v54, v49
	v_mul_f32_e32 v49, 0xbfb8aa3b, v55
	v_exp_f32_e32 v55, v49
	s_nop 0
	v_pk_add_f32 v[54:55], v[54:55], 1.0 op_sel_hi:[1,0]
	s_nop 0
	s_nop 0
	s_nop 0
	s_nop 0
	s_nop 0
	s_nop 0
	s_nop 0
	s_nop 0
	s_nop 0
	s_nop 0
	s_nop 0
	s_nop 0
	v_rcp_f32_e32 v49, v55
	s_nop 0
	s_nop 0
	s_nop 0
	s_nop 0
	s_nop 0
	s_nop 0
	s_nop 0
	s_nop 0
	s_nop 0
	s_nop 0
	s_nop 0
	v_rcp_f32_e32 v54, v54
	s_nop 0
	v_cvt_pk_bf16_f32 v49, v54, v49
	s_nop 0
	s_nop 0
	s_nop 0
	s_nop 0
	s_nop 0
	s_nop 0
	s_nop 0
	s_nop 0
	s_nop 0
	s_nop 0
	s_nop 0
	v_rcp_f32_e32 v51, v51
	s_nop 0
	s_nop 0
	s_nop 0
	s_nop 0
	s_nop 0
	s_nop 0
	s_nop 0
	s_nop 0
	s_nop 0
	s_nop 0
	s_nop 0
	v_rcp_f32_e32 v50, v50
	s_nop 0
	v_cvt_pk_bf16_f32 v50, v50, v51
	v_mul_f32_e32 v51, 0xbfb8aa3b, v52
	v_exp_f32_e32 v52, v51
	v_mul_f32_e32 v51, 0xbfb8aa3b, v53
	v_exp_f32_e32 v53, v51
	s_nop 0
	v_pk_add_f32 v[52:53], v[52:53], 1.0 op_sel_hi:[1,0]
	s_nop 0
	s_nop 0
	s_nop 0
	s_nop 0
	s_nop 0
	s_nop 0
	s_nop 0
	s_nop 0
	s_nop 0
	s_nop 0
	s_nop 0
	s_nop 0
	v_rcp_f32_e32 v51, v53
	s_nop 0
	s_nop 0
	s_nop 0
	s_nop 0
	s_nop 0
	s_nop 0
	s_nop 0
	s_nop 0
	s_nop 0
	s_nop 0
	s_nop 0
	v_rcp_f32_e32 v52, v52
	s_nop 0
	v_cvt_pk_bf16_f32 v51, v52, v51
	global_store_dwordx4 v[56:57], v[48:51], off
	v_pk_fma_f32 v[38:39], v[38:39], v[58:59], v[30:31] op_sel_hi:[1,0,1]
	s_nop 0
	v_pk_fma_f32 v[48:49], v[36:37], v[58:59], v[28:29] op_sel_hi:[1,0,1]
	v_pk_fma_f32 v[36:37], v[34:35], v[58:59], v[26:27] op_sel_hi:[1,0,1]
	v_pk_fma_f32 v[34:35], v[32:33], v[58:59], v[24:25] op_sel_hi:[1,0,1]
	v_mul_f32_e32 v32, 0xbfb8aa3b, v48
	v_mul_f32_e32 v33, 0xbfb8aa3b, v49
	v_exp_f32_e32 v32, v32
	v_exp_f32_e32 v33, v33
	v_mul_f32_e32 v34, 0xbfb8aa3b, v34
	v_mul_f32_e32 v35, 0xbfb8aa3b, v35
	v_exp_f32_e32 v34, v34
	v_pk_add_f32 v[32:33], v[32:33], 1.0 op_sel_hi:[1,0]
	v_exp_f32_e32 v35, v35
	s_nop 0
	s_nop 0
	v_pk_add_f32 v[34:35], v[34:35], 1.0 op_sel_hi:[1,0]
	s_nop 0
	s_nop 0
	s_nop 0
	s_nop 0
	s_nop 0
	s_nop 0
	s_nop 0
	s_nop 0
	v_rcp_f32_e32 v33, v33
	s_nop 0
	s_nop 0
	s_nop 0
	s_nop 0
	s_nop 0
	s_nop 0
	s_nop 0
	s_nop 0
	s_nop 0
	s_nop 0
	s_nop 0
	v_rcp_f32_e32 v32, v32
	s_nop 0
	v_cvt_pk_bf16_f32 v32, v32, v33
	v_mul_f32_e32 v33, 0xbfb8aa3b, v38
	v_exp_f32_e32 v38, v33
	v_mul_f32_e32 v33, 0xbfb8aa3b, v39
	v_exp_f32_e32 v39, v33
	s_nop 0
	v_pk_add_f32 v[38:39], v[38:39], 1.0 op_sel_hi:[1,0]
	s_nop 0
	s_nop 0
	s_nop 0
	s_nop 0
	s_nop 0
	s_nop 0
	s_nop 0
	s_nop 0
	s_nop 0
	s_nop 0
	s_nop 0
	s_nop 0
	v_rcp_f32_e32 v33, v39
	s_nop 0
	s_nop 0
	s_nop 0
	s_nop 0
	s_nop 0
	s_nop 0
	s_nop 0
	s_nop 0
	s_nop 0
	s_nop 0
	s_nop 0
	v_rcp_f32_e32 v38, v38
	s_nop 0
	v_cvt_pk_bf16_f32 v33, v38, v33
	s_nop 0
	s_nop 0
	s_nop 0
	s_nop 0
	s_nop 0
	s_nop 0
	s_nop 0
	s_nop 0
	s_nop 0
	s_nop 0
	s_nop 0
	v_rcp_f32_e32 v35, v35
	s_nop 0
	s_nop 0
	s_nop 0
	s_nop 0
	s_nop 0
	s_nop 0
	s_nop 0
	s_nop 0
	s_nop 0
	s_nop 0
	s_nop 0
	v_rcp_f32_e32 v34, v34
	s_nop 0
	v_cvt_pk_bf16_f32 v34, v34, v35
	v_mul_f32_e32 v35, 0xbfb8aa3b, v36
	v_exp_f32_e32 v36, v35
	v_mul_f32_e32 v35, 0xbfb8aa3b, v37
	v_exp_f32_e32 v37, v35
	s_nop 0
	v_pk_add_f32 v[36:37], v[36:37], 1.0 op_sel_hi:[1,0]
	s_nop 0
	s_nop 0
	s_nop 0
	s_nop 0
	s_nop 0
	s_nop 0
	s_nop 0
	s_nop 0
	s_nop 0
	s_nop 0
	s_nop 0
	s_nop 0
	v_rcp_f32_e32 v35, v37
	s_nop 0
	s_nop 0
	s_nop 0
	s_nop 0
	s_nop 0
	s_nop 0
	s_nop 0
	s_nop 0
	s_nop 0
	s_nop 0
	s_nop 0
	v_rcp_f32_e32 v36, v36
	s_nop 0
	v_cvt_pk_bf16_f32 v35, v36, v35
	global_store_dwordx4 v[56:57], v[32:35], off offset:256
	v_add_u32_e32 v56, 0xb0, v180
	v_ashrrev_i32_e32 v57, 31, v56
	v_lshlrev_b64 v[32:33], 6, v[56:57]
	v_lshl_add_u64 v[52:53], s[2:3], 0, v[32:33]
	global_load_dwordx4 v[32:35], v[52:53], off offset:16
	global_load_dwordx4 v[36:39], v[52:53], off offset:48
	global_load_dwordx4 v[48:51], v[52:53], off
	s_nop 0
	global_load_dwordx4 v[52:55], v[52:53], off offset:32
	s_waitcnt vmcnt(1)
	v_mov_b32_e32 v58, v48
	s_waitcnt vmcnt(0)
	v_mov_b32_e32 v59, v52
	v_mov_b32_e32 v52, v49
	v_pk_add_f32 v[48:49], v[58:59], v[52:53]
	v_mov_b32_e32 v52, v50
	v_mov_b32_e32 v53, v54
	v_mov_b32_e32 v54, v51
	v_pk_add_f32 v[50:51], v[52:53], v[54:55]
	s_nop 0
	v_pk_add_f32 v[48:49], v[48:49], v[50:51]
	v_mov_b32_e32 v50, v32
	v_mov_b32_e32 v51, v36
	v_mov_b32_e32 v36, v33
	v_pk_add_f32 v[32:33], v[50:51], v[36:37]
	v_mov_b32_e32 v36, v34
	v_mov_b32_e32 v37, v38
	v_mov_b32_e32 v38, v35
	v_pk_add_f32 v[34:35], v[36:37], v[38:39]
	s_nop 0
	v_pk_add_f32 v[32:33], v[32:33], v[34:35]
	s_nop 0
	v_pk_add_f32 v[32:33], v[48:49], v[32:33]
	s_nop 0
	v_add_f32_e32 v32, v32, v33
	v_fmamk_f32 v32, v32, 0x3a800000, v208
	v_cmp_gt_f32_e32 vcc, s51, v32
	v_mul_f32_e32 v33, 0x4b800000, v32
	s_nop 0
	v_cndmask_b32_e32 v32, v32, v33, vcc
	v_rsq_f32_e32 v32, v32
	s_nop 0
	v_mul_f32_e32 v33, 0x45800000, v32
	v_cndmask_b32_e32 v34, v32, v33, vcc
	v_pk_fma_f32 v[36:37], v[20:21], v[34:35], v[44:45] op_sel_hi:[1,0,1]
	v_pk_fma_f32 v[20:21], v[18:19], v[34:35], v[42:43] op_sel_hi:[1,0,1]
	v_pk_fma_f32 v[18:19], v[16:17], v[34:35], v[40:41] op_sel_hi:[1,0,1]
	v_mul_f32_e32 v16, 0xbfb8aa3b, v36
	v_mul_f32_e32 v17, 0xbfb8aa3b, v37
	v_exp_f32_e32 v16, v16
	v_exp_f32_e32 v17, v17
	v_pk_fma_f32 v[22:23], v[22:23], v[34:35], v[46:47] op_sel_hi:[1,0,1]
	v_mul_f32_e32 v18, 0xbfb8aa3b, v18
	v_mul_f32_e32 v19, 0xbfb8aa3b, v19
	v_pk_add_f32 v[16:17], v[16:17], 1.0 op_sel_hi:[1,0]
	v_exp_f32_e32 v18, v18
	s_nop 0
	s_nop 0
	v_exp_f32_e32 v19, v19
	v_lshlrev_b64 v[32:33], 11, v[56:57]
	v_lshl_add_u64 v[32:33], v[178:179], 0, v[32:33]
	s_nop 0
	s_nop 0
	s_nop 0
	s_nop 0
	s_nop 0
	s_nop 0
	s_nop 0
	s_nop 0
	v_rcp_f32_e32 v17, v17
	s_nop 0
	s_nop 0
	v_pk_add_f32 v[18:19], v[18:19], 1.0 op_sel_hi:[1,0]
	s_nop 0
	s_nop 0
	s_nop 0
	s_nop 0
	s_nop 0
	s_nop 0
	s_nop 0
	s_nop 0
	v_rcp_f32_e32 v16, v16
	s_nop 0
	v_cvt_pk_bf16_f32 v16, v16, v17
	v_mul_f32_e32 v17, 0xbfb8aa3b, v22
	v_exp_f32_e32 v22, v17
	v_mul_f32_e32 v17, 0xbfb8aa3b, v23
	v_exp_f32_e32 v23, v17
	s_nop 0
	v_pk_add_f32 v[22:23], v[22:23], 1.0 op_sel_hi:[1,0]
	s_nop 0
	s_nop 0
	s_nop 0
	s_nop 0
	s_nop 0
	s_nop 0
	s_nop 0
	s_nop 0
	s_nop 0
	s_nop 0
	s_nop 0
	s_nop 0
	v_rcp_f32_e32 v17, v23
	s_nop 0
	s_nop 0
	s_nop 0
	s_nop 0
	s_nop 0
	s_nop 0
	s_nop 0
	s_nop 0
	s_nop 0
	s_nop 0
	s_nop 0
	v_rcp_f32_e32 v22, v22
	s_nop 0
	v_cvt_pk_bf16_f32 v17, v22, v17
	s_nop 0
	s_nop 0
	s_nop 0
	s_nop 0
	s_nop 0
	s_nop 0
	s_nop 0
	s_nop 0
	s_nop 0
	s_nop 0
	s_nop 0
	v_rcp_f32_e32 v19, v19
	s_nop 0
	s_nop 0
	s_nop 0
	s_nop 0
	s_nop 0
	s_nop 0
	s_nop 0
	s_nop 0
	s_nop 0
	s_nop 0
	s_nop 0
	v_rcp_f32_e32 v18, v18
	s_nop 0
	v_cvt_pk_bf16_f32 v18, v18, v19
	v_mul_f32_e32 v19, 0xbfb8aa3b, v20
	v_exp_f32_e32 v20, v19
	v_mul_f32_e32 v19, 0xbfb8aa3b, v21
	v_exp_f32_e32 v21, v19
	s_nop 0
	v_pk_add_f32 v[20:21], v[20:21], 1.0 op_sel_hi:[1,0]
	s_nop 0
	s_nop 0
	s_nop 0
	s_nop 0
	s_nop 0
	s_nop 0
	s_nop 0
	s_nop 0
	s_nop 0
	s_nop 0
	s_nop 0
	s_nop 0
	v_rcp_f32_e32 v19, v21
	s_nop 0
	s_nop 0
	s_nop 0
	s_nop 0
	s_nop 0
	s_nop 0
	s_nop 0
	s_nop 0
	s_nop 0
	s_nop 0
	s_nop 0
	v_rcp_f32_e32 v20, v20
	s_nop 0
	v_cvt_pk_bf16_f32 v19, v20, v19
	global_store_dwordx4 v[32:33], v[16:19], off
	v_pk_fma_f32 v[14:15], v[14:15], v[34:35], v[30:31] op_sel_hi:[1,0,1]
	s_nop 0
	v_pk_fma_f32 v[16:17], v[12:13], v[34:35], v[28:29] op_sel_hi:[1,0,1]
	v_pk_fma_f32 v[12:13], v[10:11], v[34:35], v[26:27] op_sel_hi:[1,0,1]
	v_pk_fma_f32 v[10:11], v[8:9], v[34:35], v[24:25] op_sel_hi:[1,0,1]
	v_mul_f32_e32 v8, 0xbfb8aa3b, v16
	v_mul_f32_e32 v9, 0xbfb8aa3b, v17
	v_exp_f32_e32 v8, v8
	v_exp_f32_e32 v9, v9
	v_mul_f32_e32 v10, 0xbfb8aa3b, v10
	v_mul_f32_e32 v11, 0xbfb8aa3b, v11
	v_exp_f32_e32 v10, v10
	v_pk_add_f32 v[8:9], v[8:9], 1.0 op_sel_hi:[1,0]
	v_exp_f32_e32 v11, v11
	s_nop 0
	s_nop 0
	v_pk_add_f32 v[10:11], v[10:11], 1.0 op_sel_hi:[1,0]
	s_nop 0
	s_nop 0
	s_nop 0
	s_nop 0
	s_nop 0
	s_nop 0
	s_nop 0
	s_nop 0
	v_rcp_f32_e32 v9, v9
	s_nop 0
	s_nop 0
	s_nop 0
	s_nop 0
	s_nop 0
	s_nop 0
	s_nop 0
	s_nop 0
	s_nop 0
	s_nop 0
	s_nop 0
	v_rcp_f32_e32 v8, v8
	s_nop 0
	v_cvt_pk_bf16_f32 v8, v8, v9
	v_mul_f32_e32 v9, 0xbfb8aa3b, v14
	v_exp_f32_e32 v14, v9
	v_mul_f32_e32 v9, 0xbfb8aa3b, v15
	v_exp_f32_e32 v15, v9
	s_nop 0
	v_pk_add_f32 v[14:15], v[14:15], 1.0 op_sel_hi:[1,0]
	s_nop 0
	s_nop 0
	s_nop 0
	s_nop 0
	s_nop 0
	s_nop 0
	s_nop 0
	s_nop 0
	s_nop 0
	s_nop 0
	s_nop 0
	s_nop 0
	v_rcp_f32_e32 v9, v15
	s_nop 0
	s_nop 0
	s_nop 0
	s_nop 0
	s_nop 0
	s_nop 0
	s_nop 0
	s_nop 0
	s_nop 0
	s_nop 0
	s_nop 0
	v_rcp_f32_e32 v14, v14
	s_nop 0
	v_cvt_pk_bf16_f32 v9, v14, v9
	s_nop 0
	s_nop 0
	s_nop 0
	s_nop 0
	s_nop 0
	s_nop 0
	s_nop 0
	s_nop 0
	s_nop 0
	s_nop 0
	s_nop 0
	v_rcp_f32_e32 v11, v11
	s_nop 0
	s_nop 0
	s_nop 0
	s_nop 0
	s_nop 0
	s_nop 0
	s_nop 0
	s_nop 0
	s_nop 0
	s_nop 0
	s_nop 0
	v_rcp_f32_e32 v10, v10
	s_nop 0
	v_cvt_pk_bf16_f32 v10, v10, v11
	v_mul_f32_e32 v11, 0xbfb8aa3b, v12
	v_exp_f32_e32 v12, v11
	v_mul_f32_e32 v11, 0xbfb8aa3b, v13
	v_exp_f32_e32 v13, v11
	s_nop 0
	v_pk_add_f32 v[12:13], v[12:13], 1.0 op_sel_hi:[1,0]
	s_nop 0
	s_nop 0
	s_nop 0
	s_nop 0
	s_nop 0
	s_nop 0
	s_nop 0
	s_nop 0
	s_nop 0
	s_nop 0
	s_nop 0
	s_nop 0
	v_rcp_f32_e32 v11, v13
	s_nop 0
	s_nop 0
	s_mov_b64 s[14:15], -1
	s_nop 0
	s_nop 0
	s_nop 0
	s_nop 0
	s_nop 0
	s_nop 0
	s_nop 0
	s_nop 0
	v_rcp_f32_e32 v12, v12
	s_nop 0
	v_cvt_pk_bf16_f32 v11, v12, v11
	global_store_dwordx4 v[32:33], v[8:11], off offset:256
	s_andn2_b64 vcc, exec, s[42:43]
	s_cbranch_vccnz .LBB0_767
	s_andn2_b64 vcc, exec, s[0:1]
	s_cbranch_vccnz .LBB0_766
	s_barrier
	s_branch .LBB0_766
